# layer-1 adaLN GEMV units of workgroups 16-191 run inside layer-0 GLU phase idle window; GEMV weight-row loads software-pipelined
# baseline (speedup 1.0000x reference)
_Z3fwd4Args:
	s_mov_b32 s101, 0
	s_mov_b64 s[70:71], s[0:1]
	s_load_dwordx4 s[60:63], s[0:1], 0xe0
	s_add_u32 s0, s70, 0xf0
	s_addc_u32 s1, s71, 0
	s_mov_b32 s76, s2
	v_writelane_b32 v253, s0, 0
	s_nop 1
	v_writelane_b32 v253, s1, 1
	s_movk_i32 s0, 0x80
	v_cmp_gt_u32_e32 vcc, s0, v0
	s_and_saveexec_b64 s[4:5], vcc
	v_lshl_add_u32 v1, v0, 2, 0
	v_add_u32_e32 v1, 0x23e00, v1
	v_mov_b32_e32 v2, 0
	ds_write_b32 v1, v2
	s_or_b64 exec, exec, s[4:5]
	s_load_dword s3, s[70:71], 0xf0
	s_waitcnt lgkmcnt(0)
	s_add_u32 s4, s60, 0x1000
	s_addc_u32 s5, s61, 0
	s_sub_i32 s1, s63, s62
	s_cmp_lt_i32 s1, 2
	s_mov_b32 s1, 0
	s_mov_b64 s[82:83], 0x1000
	s_mov_b32 s89, 0
	s_mov_b32 s0, 0
	v_cmp_eq_u32_e32 vcc, 0, v0
	v_writelane_b32 v253, s1, 2
	s_barrier
	s_cbranch_scc1 .LBB0_7
	s_getreg_b32 s0, hwreg(HW_REG_XCC_ID, 0, 4)
	s_and_b32 s0, s0, 15
	s_and_saveexec_b64 s[6:7], vcc
	s_cbranch_execz .LBB0_6
	s_mov_b64 s[8:9], exec
	v_mbcnt_lo_u32_b32 v1, s8, 0
	v_mbcnt_hi_u32_b32 v1, s9, v1
	v_cmp_eq_u32_e32 vcc, 0, v1
	s_and_b64 s[10:11], exec, vcc
	s_mov_b64 exec, s[10:11]
	s_cbranch_execz .LBB0_6
	s_lshl_b32 s1, s0, 8
	s_bcnt1_i32_b64 s2, s[8:9]
	v_mov_b32_e32 v1, s1
	v_mov_b32_e32 v2, s2
	global_atomic_add v1, v2, s[4:5] offset:1024

.Lmy_gemv_entry:
	s_waitcnt vmcnt(0)
	v_mov_b32_e32 v8, v0
	s_mov_b64 s[6:7], s[70:71]
	s_load_dwordx2 s[4:5], s[6:7], 0xe0
	v_readlane_b32 s8, v253, 3
	v_readfirstlane_b32 s0, v8
	v_readlane_b32 s9, v253, 4
	s_cmp_lg_u64 s[78:79], 0
	s_cbranch_scc0 .Lmy_a_keep
	s_cmpk_lg_i32 s3, 0x100
	s_cbranch_scc1 .Lmy_a_keep
	s_cmpk_lt_i32 s76, 16
	s_cbranch_scc1 .Lmy_a_keep
	s_mov_b64 s[8:9], 0
.Lmy_a_keep:
	v_and_b32_e32 v16, 63, v8
	s_andn2_b64 vcc, exec, s[8:9]
	s_ashr_i32 s30, s0, 6
	s_cbranch_vccnz .LBB0_37
	v_ashrrev_i32_e32 v2, 31, v8
	v_lshrrev_b32_e32 v2, 26, v2
	s_waitcnt lgkmcnt(0)
	v_readlane_b32 s12, v255, 8
	v_add_u32_e32 v2, v8, v2
	s_load_dwordx4 s[48:51], s[6:7], 0x28
	s_load_dwordx2 s[8:9], s[6:7], 0x8
	s_load_dwordx2 s[10:11], s[6:7], 0x18
	s_mov_b32 s42, s12
	v_ashrrev_i32_e32 v6, 6, v2
	v_and_b32_e32 v2, 0xffffffc0, v2
	v_mad_u64_u32 v[4:5], s[42:43], s42, 5, v[6:7]
	s_mul_i32 s0, s12, 0xc000
	v_sub_u32_e32 v2, v8, v2
	s_waitcnt lgkmcnt(0)
	v_mov_b64_e32 v[10:11], s[4:5]
	s_mov_b32 s42, 0xc000
	v_readlane_b32 s13, v255, 9
	s_mul_i32 s46, s12, 0xc000000
	s_add_u32 s12, s50, s0
	v_ashrrev_i32_e32 v3, 31, v2
	v_mad_i64_i32 v[4:5], s[42:43], v4, s42, v[10:11]
	s_addc_u32 s13, s51, 0
	s_movk_i32 s0, 0x5000
	s_lshl_b32 s2, s30, 11
	s_mul_i32 s40, s30, 0x500
	v_lshl_add_u64 v[4:5], v[2:3], 2, v[4:5]
	v_max_i32_e32 v3, 0x4e00, v8
	v_cmp_gt_i32_e64 s[38:39], s0, v8
	s_lshl_b32 s0, s30, 9
	s_add_i32 s2, s2, 0
	s_add_i32 s40, s14, s40
	v_sub_u32_e32 v3, v3, v8
	s_mul_i32 s47, s30, 0x1800000
	v_add_u32_e32 v3, 0x1ff, v3
	s_mul_hi_i32 s0, s0, 0xc000
	s_add_u32 s46, s46, s47
	v_lshlrev_b32_e32 v10, 8, v6
	v_lshrrev_b32_e32 v6, 9, v3
	s_addc_u32 s0, 0, s0
	s_mov_b64 s[42:43], 0xaf40000
	v_add_u32_e32 v6, 1, v6
	s_add_u32 s46, s48, s46
	v_lshlrev_b32_e32 v194, 2, v16
	v_lshl_add_u64 v[4:5], v[4:5], 0, s[42:43]
	v_cmp_lt_u32_e64 s[42:43], s15, v3
	v_and_b32_e32 v3, 0xfffffe, v6
	s_addc_u32 s47, s49, s0
	v_add_u32_e32 v17, s40, v194
	s_movk_i32 s40, 0x140
	v_lshl_add_u32 v12, v2, 2, s14
	v_cmp_ne_u32_e64 s[44:45], v6, v3
	v_lshl_add_u64 v[6:7], s[46:47], 0, v[194:195]
	s_mov_b64 s[46:47], 0x54000
	v_readlane_b32 s0, v254, 30
	v_cmp_gt_i32_e64 s[40:41], s40, v8
	v_lshl_add_u32 v18, v3, 9, v8
	v_add_u32_e32 v9, 0x200, v8
	v_lshl_add_u32 v19, v8, 2, 0
	v_lshl_add_u64 v[6:7], v[6:7], 0, s[46:47]
	s_mov_b64 s[46:47], 0
	v_add_u32_e32 v20, v12, v10
	s_mov_b32 s48, s0
	s_mov_b32 s56, s76
	s_branch .LBB0_17

.LBB0_33:
	s_ashr_i32 s49, s48, 31
	v_mov_b32_e32 v21, 0
	v_lshl_add_u64 v[10:11], s[48:49], 2, v[6:7]
	s_movk_i32 s0, 0xf800
	v_mov_b32_e32 v12, 0
	v_mov_b32_e32 v13, v21
	v_mov_b32_e32 v14, 0
	v_mov_b32_e32 v15, v21
	s_mov_b32 s46, 0xfffb8000
	v_add_co_u32_e64 v24, s[46:47], s46, v10
	v_add_co_u32_e32 v22, vcc, 0xfffac000, v10
	s_nop 0
	v_addc_co_u32_e64 v25, s[46:47], -1, v11, s[46:47]
	s_mov_b32 s46, 0xfffc4000
	s_nop 0
	v_add_co_u32_e64 v26, s[46:47], s46, v10
	v_addc_co_u32_e32 v23, vcc, -1, v11, vcc
	s_nop 0
	v_addc_co_u32_e64 v27, s[46:47], -1, v11, s[46:47]
	s_mov_b32 s46, 0xfffd0000
	s_nop 0
	v_add_co_u32_e64 v28, s[46:47], s46, v10
	s_nop 1
	v_addc_co_u32_e64 v29, s[46:47], -1, v11, s[46:47]
	s_mov_b32 s46, 0xfffdc000
	s_nop 0
	v_add_co_u32_e64 v30, s[46:47], s46, v10
	s_nop 1
	v_addc_co_u32_e64 v31, s[46:47], -1, v11, s[46:47]
	s_mov_b32 s46, 0xfffe8000
	s_nop 0
	v_add_co_u32_e64 v32, s[46:47], s46, v10
	s_nop 1
	v_addc_co_u32_e64 v33, s[46:47], -1, v11, s[46:47]
	s_mov_b32 s46, 0xffff4000
	s_nop 0
	v_add_co_u32_e64 v34, s[46:47], s46, v10
	s_nop 1
	v_addc_co_u32_e64 v35, s[46:47], -1, v11, s[46:47]
	global_load_dword v62, v[24:25], off
	global_load_dword v64, v[26:27], off
	global_load_dword v66, v[28:29], off
	global_load_dword v68, v[30:31], off
	global_load_dword v70, v[22:23], off
	global_load_dword v72, v[32:33], off
	global_load_dword v74, v[34:35], off
	global_load_dword v76, v[10:11], off
.LBB0_34:
	s_waitcnt vmcnt(0)
	v_mov_b32_e32 v82, v62
	v_mov_b32_e32 v84, v64
	v_mov_b32_e32 v86, v66
	v_mov_b32_e32 v88, v68
	v_mov_b32_e32 v90, v70
	v_mov_b32_e32 v92, v72
	v_mov_b32_e32 v94, v74
	v_mov_b32_e32 v96, v76
	s_mov_b64 s[46:47], 0x60000
	v_lshl_add_u64 v[10:11], v[10:11], 0, s[46:47]
	s_cmp_eq_u32 s0, 0xffffffe0
	s_cbranch_scc1 .Lmy_gemv_nopf
	s_mov_b32 s46, 0xfffb8000
	v_add_co_u32_e64 v24, s[46:47], s46, v10
	v_add_co_u32_e32 v22, vcc, 0xfffac000, v10
	s_nop 0
	v_addc_co_u32_e64 v25, s[46:47], -1, v11, s[46:47]
	s_mov_b32 s46, 0xfffc4000
	s_nop 0
	v_add_co_u32_e64 v26, s[46:47], s46, v10
	v_addc_co_u32_e32 v23, vcc, -1, v11, vcc
	s_nop 0
	v_addc_co_u32_e64 v27, s[46:47], -1, v11, s[46:47]
	s_mov_b32 s46, 0xfffd0000
	s_nop 0
	v_add_co_u32_e64 v28, s[46:47], s46, v10
	s_nop 1
	v_addc_co_u32_e64 v29, s[46:47], -1, v11, s[46:47]
	s_mov_b32 s46, 0xfffdc000
	s_nop 0
	v_add_co_u32_e64 v30, s[46:47], s46, v10
	s_nop 1
	v_addc_co_u32_e64 v31, s[46:47], -1, v11, s[46:47]
	s_mov_b32 s46, 0xfffe8000
	s_nop 0
	v_add_co_u32_e64 v32, s[46:47], s46, v10
	s_nop 1
	v_addc_co_u32_e64 v33, s[46:47], -1, v11, s[46:47]
	s_mov_b32 s46, 0xffff4000
	s_nop 0
	v_add_co_u32_e64 v34, s[46:47], s46, v10
	s_nop 1
	v_addc_co_u32_e64 v35, s[46:47], -1, v11, s[46:47]
	global_load_dword v62, v[24:25], off
	global_load_dword v64, v[26:27], off
	global_load_dword v66, v[28:29], off
	global_load_dword v68, v[30:31], off
	global_load_dword v70, v[22:23], off
	global_load_dword v72, v[32:33], off
	global_load_dword v74, v[34:35], off
	global_load_dword v76, v[10:11], off
.Lmy_gemv_nopf:
	s_add_i32 s46, s2, s0
	v_mov_b32_e32 v50, s46
	s_add_i32 s49, s46, 0x10800
	s_add_i32 s50, s46, 0x10810
	ds_read_b128 v[22:25], v50 offset:2048
	ds_read_b128 v[26:29], v50 offset:2064
	v_mov_b32_e32 v54, s49
	ds_read_b128 v[30:33], v50 offset:18432
	ds_read_b128 v[34:37], v50 offset:18448
	ds_read_b128 v[38:41], v50 offset:34816
	ds_read_b128 v[42:45], v50 offset:34832
	ds_read_b128 v[46:49], v50 offset:51200
	ds_read_b128 v[50:53], v50 offset:51216
	v_mov_b32_e32 v58, s50
	ds_read_b128 v[54:57], v54
	ds_read_b128 v[58:61], v58
	s_waitcnt lgkmcnt(9)
	v_mov_b32_e32 v78, v22
	s_waitcnt lgkmcnt(7)
	v_mov_b32_e32 v79, v30
	s_waitcnt lgkmcnt(5)
	v_mov_b32_e32 v80, v38
	s_waitcnt lgkmcnt(3)
	v_mov_b32_e32 v81, v46
	v_mov_b32_e32 v30, v23
	v_mov_b32_e32 v46, v39
	v_mov_b32_e32 v22, v24
	v_mov_b32_e32 v23, v32
	v_mov_b32_e32 v38, v40
	v_mov_b32_e32 v39, v48
	v_mov_b32_e32 v32, v25
	v_mov_b32_e32 v48, v41
	v_mov_b32_e32 v24, v26
	v_mov_b32_e32 v25, v34
	v_mov_b32_e32 v40, v42
	s_waitcnt lgkmcnt(2)
	v_mov_b32_e32 v41, v50
	v_mov_b32_e32 v34, v27
	v_mov_b32_e32 v50, v43
	v_mov_b32_e32 v26, v28
	v_mov_b32_e32 v27, v36
	v_mov_b32_e32 v42, v44
	v_mov_b32_e32 v43, v52
	s_add_i32 s0, s0, 32
	v_mov_b32_e32 v36, v29
	v_mov_b32_e32 v52, v45
	s_cmp_eq_u32 s0, 0
	v_pk_fma_f32 v[12:13], v[90:91], v[78:79], v[12:13] op_sel_hi:[0,1,1]
	v_pk_fma_f32 v[14:15], v[90:91], v[80:81], v[14:15] op_sel_hi:[0,1,1]
	s_waitcnt lgkmcnt(1)
	v_fmac_f32_e32 v21, v90, v54
	v_pk_fma_f32 v[12:13], v[82:83], v[30:31], v[12:13] op_sel_hi:[0,1,1]
	v_pk_fma_f32 v[14:15], v[82:83], v[46:47], v[14:15] op_sel_hi:[0,1,1]
	v_fmac_f32_e32 v21, v82, v55
	v_pk_fma_f32 v[12:13], v[84:85], v[22:23], v[12:13] op_sel_hi:[0,1,1]
	v_pk_fma_f32 v[14:15], v[84:85], v[38:39], v[14:15] op_sel_hi:[0,1,1]
	v_fmac_f32_e32 v21, v84, v56
	v_pk_fma_f32 v[12:13], v[86:87], v[32:33], v[12:13] op_sel_hi:[0,1,1]
	v_pk_fma_f32 v[14:15], v[86:87], v[48:49], v[14:15] op_sel_hi:[0,1,1]
	v_fmac_f32_e32 v21, v86, v57
	v_pk_fma_f32 v[12:13], v[88:89], v[24:25], v[12:13] op_sel_hi:[0,1,1]
	v_pk_fma_f32 v[14:15], v[88:89], v[40:41], v[14:15] op_sel_hi:[0,1,1]
	s_waitcnt lgkmcnt(0)
	v_fmac_f32_e32 v21, v88, v58
	v_pk_fma_f32 v[12:13], v[92:93], v[34:35], v[12:13] op_sel_hi:[0,1,1]
	v_pk_fma_f32 v[14:15], v[92:93], v[50:51], v[14:15] op_sel_hi:[0,1,1]
	v_fmac_f32_e32 v21, v92, v59
	v_pk_fma_f32 v[12:13], v[94:95], v[26:27], v[12:13] op_sel_hi:[0,1,1]
	v_pk_fma_f32 v[14:15], v[94:95], v[42:43], v[14:15] op_sel_hi:[0,1,1]
	v_fmac_f32_e32 v21, v94, v60
	v_pk_fma_f32 v[12:13], v[96:97], v[36:37], v[12:13] op_sel_hi:[0,1,1]
	v_pk_fma_f32 v[14:15], v[96:97], v[52:53], v[14:15] op_sel_hi:[0,1,1]
	v_fmac_f32_e32 v21, v96, v61
	s_cbranch_scc0 .LBB0_34
	ds_write2st64_b32 v17, v12, v13 offset1:1
	ds_write2st64_b32 v17, v14, v15 offset0:2 offset1:3
	ds_write_b32 v17, v21 offset:1024
	s_waitcnt lgkmcnt(0)
	s_barrier
	s_and_saveexec_b64 s[46:47], s[40:41]
	s_cbranch_execz .LBB0_16
	s_lshl_b32 s50, s56, 6
	v_add_u32_e32 v10, s50, v2
	v_ashrrev_i32_e32 v11, 31, v10
	v_lshl_add_u64 v[10:11], v[10:11], 2, s[12:13]
	global_load_dword v21, v[10:11], off
	ds_read2st64_b32 v[10:11], v20 offset1:5
	ds_read2st64_b32 v[12:13], v20 offset0:10 offset1:15
	ds_read2st64_b32 v[14:15], v20 offset0:20 offset1:25
	ds_read2st64_b32 v[22:23], v20 offset0:30 offset1:35
	s_ashr_i32 s51, s50, 31
	s_waitcnt lgkmcnt(3)
	v_add_f32_e32 v10, 0, v10
	v_add_f32_e32 v10, v10, v11
	s_waitcnt lgkmcnt(2)
	v_add_f32_e32 v10, v10, v12
	v_add_f32_e32 v10, v10, v13
	s_waitcnt lgkmcnt(1)
	v_add_f32_e32 v10, v10, v14
	v_add_f32_e32 v10, v10, v15
	s_waitcnt lgkmcnt(0)
	v_add_f32_e32 v10, v10, v22
	v_add_f32_e32 v10, v10, v23
	s_waitcnt vmcnt(0)
	v_add_f32_e32 v12, v10, v21
	v_lshl_add_u64 v[10:11], s[50:51], 2, v[4:5]
	global_store_dword v[10:11], v12, off
	s_branch .LBB0_16
.LBB0_37:
	v_readlane_b32 s0, v253, 5
	s_add_i32 s2, s30, s0
	s_waitcnt lgkmcnt(0)
	s_barrier
	s_cmp_eq_u32 s101, 0x5a5a
	s_cbranch_scc0 .Lmy_a_cont
	s_mov_b32 s101, 0
	s_branch .Lmy_tramp_ret
.Lmy_a_cont:
	s_cmpk_gt_i32 s2, 0x453f
	s_cbranch_scc1 .LBB0_88
	s_load_dwordx2 s[8:9], s[6:7], 0x38
	v_readlane_b32 s12, v255, 8
	s_load_dwordx2 s[10:11], s[6:7], 0xc8
	s_nop 0
	s_load_dwordx2 s[6:7], s[6:7], 0xa8
	v_readlane_b32 s13, v255, 9
	s_mul_i32 s0, s12, 0xd080000
	s_mov_b32 s13, s89
	s_waitcnt lgkmcnt(0)
	s_add_u32 s42, s8, s0
	s_addc_u32 s43, s9, 0
	s_lshl_b64 s[8:9], s[12:13], 26
	s_add_u32 s44, s10, s8
	s_addc_u32 s45, s11, s9
	s_lshl_b64 s[8:9], s[12:13], 22
	s_add_u32 s46, s6, s8
	s_addc_u32 s47, s7, s9
	s_lshl_b64 s[6:7], s[12:13], 21
	s_add_u32 s6, s4, s6
	s_mov_b32 s0, s12
	s_addc_u32 s7, s5, s7
	v_writelane_b32 v255, s0, 8
	s_lshl_b64 s[8:9], s[12:13], 25
	s_add_u32 s8, s4, s8
	v_writelane_b32 v255, s1, 9
	s_mul_i32 s0, s30, 0x4400
	s_addc_u32 s9, s5, s9
	s_add_i32 s10, s0, 0
	v_lshrrev_b32_e32 v11, 4, v16
	v_mov_b32_e32 v2, s10
	s_movk_i32 s11, 0x110
	v_and_b32_e32 v3, 7, v8
	v_mad_u32_u24 v31, v11, s11, v2
	v_lshrrev_b32_e32 v42, 3, v16
	s_movk_i32 s11, 0x880
	v_lshlrev_b32_e32 v5, 2, v3
	v_mad_u32_u24 v4, v3, s11, v2
	v_xor_b32_e32 v6, v5, v42
	v_lshl_add_u32 v43, v6, 2, v4
	v_bitop3_b32 v6, v42, v5, 8 bitop3:0x36
	v_lshl_add_u32 v45, v6, 2, v4
	v_bitop3_b32 v6, v42, v5, 16 bitop3:0x36
	v_lshl_add_u32 v47, v6, 2, v4
	v_bitop3_b32 v6, v42, v5, 24 bitop3:0x36
	v_lshl_add_u32 v49, v6, 2, v4
	v_bitop3_b32 v6, v42, v5, 32 bitop3:0x36
	v_lshlrev_b32_e32 v12, 3, v16
	v_lshl_add_u32 v51, v6, 2, v4
	v_bitop3_b32 v6, v42, v5, 40 bitop3:0x36
	v_and_b32_e32 v12, 56, v12
	v_lshlrev_b32_e32 v194, 4, v3
	v_lshl_add_u32 v53, v6, 2, v4
	v_bitop3_b32 v6, v42, v5, 48 bitop3:0x36
	v_mul_u32_u24_e32 v14, 0x84, v12
	v_lshlrev_b32_e32 v12, 1, v12
	v_mov_b32_e32 v13, v195
	v_lshlrev_b32_e32 v15, 2, v42
	v_lshl_add_u32 v55, v6, 2, v4
	v_lshrrev_b32_e32 v6, 5, v16
	v_lshl_add_u64 v[12:13], s[4:5], 0, v[12:13]
	v_add3_u32 v58, s10, v14, v15
	v_lshl_add_u64 v[14:15], s[4:5], 0, v[194:195]
	s_mov_b64 s[4:5], 0x100000
	v_lshl_add_u64 v[2:3], s[6:7], 0, v[194:195]
	s_mov_b64 s[6:7], 0xab00000
	v_bitop3_b32 v5, v42, v5, 56 bitop3:0x36
	v_and_b32_e32 v17, 31, v8
	v_lshl_add_u64 v[14:15], v[14:15], 0, s[4:5]
	s_mul_i32 s4, s30, 0xfff2f800
	v_readlane_b32 s5, v254, 24
	v_mul_u32_u24_e32 v21, 0x84, v6
	v_and_b32_e32 v7, 15, v8
	v_lshl_add_u64 v[2:3], v[2:3], 0, s[6:7]
	v_or_b32_e32 v44, 8, v42
	v_or_b32_e32 v46, 16, v42
	v_or_b32_e32 v48, 24, v42
	v_lshl_add_u32 v57, v5, 2, v4
	v_lshl_add_u64 v[4:5], s[8:9], 0, v[194:195]
	s_mov_b64 s[6:7], 0x6b00000
	v_lshlrev_b32_e32 v19, 2, v17
	s_add_i32 s4, s4, s5
	v_or_b32_e32 v21, s0, v21
	s_mul_i32 s30, s30, 0xd0800
	s_mul_i32 s0, s76, 0x684000
	v_lshlrev_b32_e32 v9, 2, v7
	v_lshlrev_b32_e32 v34, 4, v7
	v_lshl_add_u64 v[4:5], v[4:5], 0, s[6:7]
	v_add_u32_e32 v10, s10, v19
	s_mov_b64 s[6:7], 0xaf00000
	v_lshlrev_b32_e32 v16, 12, v42
	v_lshlrev_b32_e32 v18, 12, v44
	v_lshlrev_b32_e32 v20, 12, v46
	v_lshlrev_b32_e32 v22, 12, v48
	v_cmp_lt_u32_e64 s[38:39], 7, v7
	v_mov_b32_e32 v7, s4
	s_movk_i32 s4, 0xcbe0
	v_add3_u32 v61, v21, v19, 0
	s_add_i32 s0, s0, s30
	v_mul_u32_u24_e32 v19, 0x3420, v6
	v_xor_b32_e32 v35, 16, v34
	v_xor_b32_e32 v36, 32, v34
	v_xor_b32_e32 v37, 48, v34
	v_xor_b32_e32 v38, 64, v34
	v_xor_b32_e32 v39, 0x50, v34
	v_xor_b32_e32 v40, 0x60, v34
	v_xor_b32_e32 v41, 0x70, v34
	v_or_b32_e32 v50, 32, v42
	v_or_b32_e32 v52, 40, v42
	v_or_b32_e32 v54, 48, v42
	v_or_b32_e32 v56, 56, v42
	v_or_b32_e32 v8, 0x1c00, v17
	v_lshl_add_u64 v[12:13], v[12:13], 0, s[6:7]
	v_subrev_u32_e32 v59, 32, v9
	v_mad_i32_i24 v60, v6, s4, v7
	v_mov_b32_e32 v7, v6
	v_add3_u32 v62, s0, v19, v17
	s_mov_b32 s8, 0
	v_lshlrev_b32_e32 v16, 1, v16
	v_lshlrev_b32_e32 v18, 1, v18
	v_lshlrev_b32_e32 v20, 1, v20
	v_lshlrev_b32_e32 v22, 1, v22
	s_branch .LBB0_41

.Lpb_next:
	s_add_i32 s65, s65, s3
	s_cmpk_lt_i32 s65, 0x440
	s_cbranch_scc1 .Lpb_loop
	s_branch .LBB0_178
	s_nop 0
	s_nop 0
	s_nop 0
	s_nop 0
	s_nop 0
	s_nop 0
	s_nop 0
	s_nop 0
	s_nop 0
	s_nop 0
	s_nop 0
	s_nop 0
	s_nop 0
	s_nop 0
	s_nop 0
	s_nop 0
	s_nop 0
	s_nop 0
	s_nop 0
	s_nop 0
	s_nop 0
	s_branch .LBB0_178
	s_nop 0
	s_nop 0
	s_nop 0
	s_nop 0
	s_nop 0
	s_nop 0
	s_nop 0
	s_nop 0
	s_nop 0
	s_nop 0
	s_nop 0
	s_nop 0
	s_nop 0
	s_nop 0
	s_nop 0
	s_nop 0
	s_nop 0
	s_nop 0
	s_nop 0
	s_nop 0
	s_nop 0
	s_nop 0
	s_nop 0
	s_nop 0
	s_nop 0
	s_nop 0
	s_nop 0
	s_nop 0
	s_nop 0
	s_nop 0
	s_nop 0
	s_nop 0
	s_nop 0
	s_nop 0
	s_nop 0
	s_nop 0
	s_nop 0
	s_nop 0
	s_nop 0
	s_nop 0
.LBB0_178:
	v_readlane_b32 s0, v255, 10
	v_readlane_b32 s60, v255, 0
	s_add_i32 s0, s0, 2
	v_readlane_b32 s63, v255, 3
	v_readlane_b32 s62, v255, 2
	s_cmp_ge_i32 s0, s63
	s_barrier
	v_readlane_b32 s61, v255, 1
	s_cbranch_scc1 .LBB0_190
	s_waitcnt vmcnt(0)
	s_barrier
	s_mov_b64 s[4:5], exec
	v_readlane_b32 s6, v254, 56
	v_readlane_b32 s7, v254, 57
	v_readlane_b32 s60, v255, 6
	s_and_b64 s[6:7], s[4:5], s[6:7]
	v_readlane_b32 s61, v255, 7
	s_mov_b64 exec, s[6:7]
	s_cbranch_execz .LBB0_228
	v_readlane_b32 s2, v253, 2
	s_waitcnt vmcnt(0) expcnt(0) lgkmcnt(0)
	s_nop 0
	v_mov_b32_e32 v2, s2
	ds_read_b32 v4, v2
	ds_read_b32 v2, v2 offset:4
	s_waitcnt lgkmcnt(1)
	v_cmp_ne_u32_e32 vcc, 0, v4
	s_cbranch_vccnz .LBB0_196
	v_readlane_b32 s8, v253, 0
	v_readlane_b32 s9, v253, 1
	s_load_dwordx2 s[6:7], s[8:9], 0x4
	s_mov_b32 s12, 1
	s_waitcnt lgkmcnt(0)
	s_mul_i32 s2, s6, s3
	s_mul_i32 s2, s2, s7
	s_branch .LBB0_183

.LBB0_494:
	s_nop 7
	v_cndmask_b32_e64 v35, v36, 0, s[56:57]
	v_cndmask_b32_e64 v36, 0, v37, s[58:59]
	v_cvt_pk_bf16_f32 v36, v35, v36
	v_cndmask_b32_e64 v35, v38, 0, s[60:61]
	v_cndmask_b32_e64 v37, v39, 0, s[62:63]
	v_cvt_pk_bf16_f32 v37, v35, v37
	ds_write_b64 v116, v[36:37] offset:64
	s_andn2_b64 vcc, exec, s[6:7]
	v_mov_b32_e32 v35, 0
	v_mov_b32_e32 v36, 0
	v_mov_b32_e32 v37, 0
	s_cbranch_vccnz .LBB0_489
	v_add_u32_e32 v38, v132, v117
	ds_read_b128 v[34:37], v38 offset:17408
	s_waitcnt lgkmcnt(0)
	v_mfma_f32_16x16x32_bf16 v[30:33], v[34:37], v[30:33], 0
	ds_read_b128 v[34:37], v38 offset:17472
	s_waitcnt lgkmcnt(0)
	v_mfma_f32_16x16x32_bf16 v[26:29], v[34:37], v[26:29], v[30:33]
	s_nop 4
	ds_read_b128 v[30:33], v38 offset:17536
	s_waitcnt lgkmcnt(0)
	v_mfma_f32_16x16x32_bf16 v[22:25], v[30:33], v[22:25], v[26:29]
	s_nop 2
	ds_read_b128 v[26:29], v38 offset:17600
	s_waitcnt lgkmcnt(0)
	v_mfma_f32_16x16x32_bf16 v[34:37], v[26:29], v[18:21], v[22:25]
	s_branch .LBB0_489
.Lmy_tramp_call:
	s_branch .Lmy_gemv_entry
.Lmy_tramp_ret:
	s_branch .Lmy_gemv_ret
.LBB0_496:
	s_setprio 0
	v_readlane_b32 s60, v255, 0
	v_readlane_b32 s61, v255, 1
	v_readlane_b32 s96, v254, 60
	v_readlane_b32 s70, v254, 62
	v_readlane_b32 s60, v255, 6
	s_mov_b64 s[4:5], 0
	v_readlane_b32 s97, v254, 61
	v_readlane_b32 s71, v254, 63
	v_readlane_b32 s62, v255, 2
	v_readlane_b32 s63, v255, 3
	v_readlane_b32 s61, v255, 7

.LBB0_695:
	v_lshl_add_u32 v148, s6, 8, v150
	s_lshl_b32 s0, s4, 8
	v_or_b32_e32 v149, s0, v152
	v_mov_b32_e32 v181, 0
	v_lshlrev_b32_e32 v180, 11, v148
	v_lshl_add_u32 v180, v149, 1, v180
	v_lshl_add_u64 v[142:143], s[40:41], 0, v[180:181]
	v_lshlrev_b32_e32 v180, 2, v149
	v_lshl_add_u64 v[178:179], s[46:47], 0, v[180:181]
	global_load_dwordx4 v[154:157], v[178:179], off
	global_load_dwordx4 v[158:161], v[178:179], off offset:16
	global_load_dwordx4 v[162:165], v[178:179], off offset:512
	global_load_dwordx4 v[166:169], v[178:179], off offset:528
	s_add_i32 s4, s0, 0x2400
	s_ashr_i32 s0, s4, 9
	s_mul_hi_i32 s4, s0, 0x1100000
	s_mul_i32 s0, s0, 0x1100000
	s_add_u32 s58, s65, s0
	s_addc_u32 s59, s66, s4
	v_and_b32_e32 v180, 0x1ff, v149
	v_lshlrev_b32_e32 v180, 1, v180
	v_lshl_add_u32 v180, v148, 10, v180
	v_lshl_add_u64 v[144:145], s[58:59], 0, v[180:181]
	v_lshlrev_b32_e32 v180, 13, v148
	v_lshl_add_u32 v180, v149, 1, v180
	v_add_u32_e32 v180, 0x1000, v180
	v_lshl_add_u64 v[146:147], s[44:45], 0, v[180:181]
	global_load_dwordx4 v[170:173], v[142:143], off
	global_load_dwordx4 v[174:177], v[144:145], off
	s_waitcnt vmcnt(2)
	v_pk_add_f32 v[126:127], v[126:127], v[154:155]
	v_pk_add_f32 v[122:123], v[122:123], v[158:159]
	v_pk_add_f32 v[128:129], v[128:129], v[156:157]
	v_pk_add_f32 v[124:125], v[124:125], v[160:161]
	v_pk_add_f32 v[118:119], v[118:119], v[162:163]
	v_pk_add_f32 v[114:115], v[114:115], v[166:167]
	v_pk_add_f32 v[120:121], v[120:121], v[164:165]
	v_pk_add_f32 v[116:117], v[116:117], v[168:169]
	v_pk_add_f32 v[110:111], v[110:111], v[154:155]
	v_pk_add_f32 v[106:107], v[106:107], v[158:159]
	v_pk_add_f32 v[112:113], v[112:113], v[156:157]
	v_pk_add_f32 v[108:109], v[108:109], v[160:161]
	v_pk_add_f32 v[102:103], v[102:103], v[162:163]
	v_pk_add_f32 v[98:99], v[98:99], v[166:167]
	v_pk_add_f32 v[104:105], v[104:105], v[164:165]
	v_pk_add_f32 v[100:101], v[100:101], v[168:169]
	v_pk_add_f32 v[94:95], v[94:95], v[154:155]
	v_pk_add_f32 v[90:91], v[90:91], v[158:159]
	v_pk_add_f32 v[96:97], v[96:97], v[156:157]
	v_pk_add_f32 v[92:93], v[92:93], v[160:161]
	v_pk_add_f32 v[86:87], v[86:87], v[162:163]
	v_pk_add_f32 v[82:83], v[82:83], v[166:167]
	v_pk_add_f32 v[88:89], v[88:89], v[164:165]
	v_pk_add_f32 v[84:85], v[84:85], v[168:169]
	v_pk_add_f32 v[78:79], v[78:79], v[154:155]
	v_pk_add_f32 v[74:75], v[74:75], v[158:159]
	v_pk_add_f32 v[80:81], v[80:81], v[156:157]
	v_pk_add_f32 v[76:77], v[76:77], v[160:161]
	v_pk_add_f32 v[70:71], v[70:71], v[162:163]
	v_pk_add_f32 v[66:67], v[66:67], v[166:167]
	v_pk_add_f32 v[72:73], v[72:73], v[164:165]
	v_pk_add_f32 v[68:69], v[68:69], v[168:169]
	v_pk_add_f32 v[62:63], v[62:63], v[154:155]
	v_pk_add_f32 v[58:59], v[58:59], v[158:159]
	v_pk_add_f32 v[64:65], v[64:65], v[156:157]
	v_pk_add_f32 v[60:61], v[60:61], v[160:161]
	v_pk_add_f32 v[54:55], v[54:55], v[162:163]
	v_pk_add_f32 v[50:51], v[50:51], v[166:167]
	v_pk_add_f32 v[56:57], v[56:57], v[164:165]
	v_pk_add_f32 v[52:53], v[52:53], v[168:169]
	v_pk_add_f32 v[46:47], v[46:47], v[154:155]
	v_pk_add_f32 v[42:43], v[42:43], v[158:159]
	v_pk_add_f32 v[48:49], v[48:49], v[156:157]
	v_pk_add_f32 v[44:45], v[44:45], v[160:161]
	v_pk_add_f32 v[38:39], v[38:39], v[162:163]
	v_pk_add_f32 v[34:35], v[34:35], v[166:167]
	v_pk_add_f32 v[40:41], v[40:41], v[164:165]
	v_pk_add_f32 v[36:37], v[36:37], v[168:169]
	v_pk_add_f32 v[30:31], v[30:31], v[154:155]
	v_pk_add_f32 v[26:27], v[26:27], v[158:159]
	v_pk_add_f32 v[32:33], v[32:33], v[156:157]
	v_pk_add_f32 v[28:29], v[28:29], v[160:161]
	v_pk_add_f32 v[22:23], v[22:23], v[162:163]
	v_pk_add_f32 v[18:19], v[18:19], v[166:167]
	v_pk_add_f32 v[24:25], v[24:25], v[164:165]
	v_pk_add_f32 v[20:21], v[20:21], v[168:169]
	v_pk_add_f32 v[14:15], v[14:15], v[154:155]
	v_pk_add_f32 v[10:11], v[10:11], v[158:159]
	v_pk_add_f32 v[16:17], v[16:17], v[156:157]
	v_pk_add_f32 v[12:13], v[12:13], v[160:161]
	v_pk_add_f32 v[6:7], v[6:7], v[162:163]
	v_pk_add_f32 v[2:3], v[2:3], v[166:167]
	v_pk_add_f32 v[8:9], v[8:9], v[164:165]
	v_pk_add_f32 v[4:5], v[4:5], v[168:169]
	global_load_dwordx4 v[154:157], v[142:143], off offset:256
	global_load_dwordx4 v[158:161], v[144:145], off offset:256
	s_mov_b64 s[58:59], 0x8000
	v_lshl_add_u64 v[142:143], v[142:143], 0, s[58:59]
	s_mov_b64 s[58:59], 0x4000
	v_lshl_add_u64 v[144:145], v[144:145], 0, s[58:59]
	global_load_dwordx4 v[162:165], v[142:143], off
	global_load_dwordx4 v[166:169], v[144:145], off
	s_waitcnt vmcnt(4)
	v_lshlrev_b32_e32 v178, 16, v170
	v_and_b32_e32 v170, 0xffff0000, v170
	v_lshlrev_b32_e32 v179, 16, v174
	v_and_b32_e32 v174, 0xffff0000, v174
	v_mul_f32_e32 v126, 0xbfb8aa3b, v126
	v_mul_f32_e32 v127, 0xbfb8aa3b, v127
	v_mul_f32_e32 v180, 0xbfb8aa3b, v179
	v_mul_f32_e32 v181, 0xbfb8aa3b, v174
	v_exp_f32_e32 v126, v126
	v_exp_f32_e32 v127, v127
	v_exp_f32_e32 v180, v180
	v_exp_f32_e32 v181, v181
	v_add_f32_e32 v126, 1.0, v126
	v_add_f32_e32 v127, 1.0, v127
	v_add_f32_e32 v180, 1.0, v180
	v_add_f32_e32 v181, 1.0, v181
	v_rcp_f32_e32 v126, v126
	v_rcp_f32_e32 v127, v127
	v_rcp_f32_e32 v180, v180
	v_rcp_f32_e32 v181, v181
	v_mul_f32_e32 v126, v126, v178
	v_mul_f32_e32 v127, v127, v170
	v_mul_f32_e32 v180, v180, v179
	v_mul_f32_e32 v181, v181, v174
	v_mul_f32_e32 v126, v126, v180
	v_mul_f32_e32 v127, v127, v181
	v_lshlrev_b32_e32 v178, 16, v171
	v_and_b32_e32 v171, 0xffff0000, v171
	v_lshlrev_b32_e32 v179, 16, v175
	v_and_b32_e32 v175, 0xffff0000, v175
	v_mul_f32_e32 v128, 0xbfb8aa3b, v128
	v_mul_f32_e32 v129, 0xbfb8aa3b, v129
	v_mul_f32_e32 v180, 0xbfb8aa3b, v179
	v_mul_f32_e32 v181, 0xbfb8aa3b, v175
	v_exp_f32_e32 v128, v128
	v_exp_f32_e32 v129, v129
	v_exp_f32_e32 v180, v180
	v_exp_f32_e32 v181, v181
	v_add_f32_e32 v128, 1.0, v128
	v_add_f32_e32 v129, 1.0, v129
	v_add_f32_e32 v180, 1.0, v180
	v_add_f32_e32 v181, 1.0, v181
	v_rcp_f32_e32 v128, v128
	v_rcp_f32_e32 v129, v129
	v_rcp_f32_e32 v180, v180
	v_rcp_f32_e32 v181, v181
	v_mul_f32_e32 v128, v128, v178
	v_mul_f32_e32 v129, v129, v171
	v_mul_f32_e32 v180, v180, v179
	v_mul_f32_e32 v181, v181, v175
	v_mul_f32_e32 v128, v128, v180
	v_mul_f32_e32 v129, v129, v181
	v_lshlrev_b32_e32 v178, 16, v172
	v_and_b32_e32 v172, 0xffff0000, v172
	v_lshlrev_b32_e32 v179, 16, v176
	v_and_b32_e32 v176, 0xffff0000, v176
	v_mul_f32_e32 v122, 0xbfb8aa3b, v122
	v_mul_f32_e32 v123, 0xbfb8aa3b, v123
	v_mul_f32_e32 v180, 0xbfb8aa3b, v179
	v_mul_f32_e32 v181, 0xbfb8aa3b, v176
	v_exp_f32_e32 v122, v122
	v_exp_f32_e32 v123, v123
	v_exp_f32_e32 v180, v180
	v_exp_f32_e32 v181, v181
	v_add_f32_e32 v122, 1.0, v122
	v_add_f32_e32 v123, 1.0, v123
	v_add_f32_e32 v180, 1.0, v180
	v_add_f32_e32 v181, 1.0, v181
	v_rcp_f32_e32 v122, v122
	v_rcp_f32_e32 v123, v123
	v_rcp_f32_e32 v180, v180
	v_rcp_f32_e32 v181, v181
	v_mul_f32_e32 v122, v122, v178
	v_mul_f32_e32 v123, v123, v172
	v_mul_f32_e32 v180, v180, v179
	v_mul_f32_e32 v181, v181, v176
	v_mul_f32_e32 v122, v122, v180
	v_mul_f32_e32 v123, v123, v181
	v_lshlrev_b32_e32 v178, 16, v173
	v_and_b32_e32 v173, 0xffff0000, v173
	v_lshlrev_b32_e32 v179, 16, v177
	v_and_b32_e32 v177, 0xffff0000, v177
	v_mul_f32_e32 v124, 0xbfb8aa3b, v124
	v_mul_f32_e32 v125, 0xbfb8aa3b, v125
	v_mul_f32_e32 v180, 0xbfb8aa3b, v179
	v_mul_f32_e32 v181, 0xbfb8aa3b, v177
	v_exp_f32_e32 v124, v124
	v_exp_f32_e32 v125, v125
	v_exp_f32_e32 v180, v180
	v_exp_f32_e32 v181, v181
	v_add_f32_e32 v124, 1.0, v124
	v_add_f32_e32 v125, 1.0, v125
	v_add_f32_e32 v180, 1.0, v180
	v_add_f32_e32 v181, 1.0, v181
	v_rcp_f32_e32 v124, v124
	v_rcp_f32_e32 v125, v125
	v_rcp_f32_e32 v180, v180
	v_rcp_f32_e32 v181, v181
	v_mul_f32_e32 v124, v124, v178
	v_mul_f32_e32 v125, v125, v173
	v_mul_f32_e32 v180, v180, v179
	v_mul_f32_e32 v181, v181, v177
	v_mul_f32_e32 v124, v124, v180
	v_mul_f32_e32 v125, v125, v181
	v_cvt_pk_bf16_f32 v126, v126, v127
	v_cvt_pk_bf16_f32 v127, v128, v129
	v_cvt_pk_bf16_f32 v128, v122, v123
	v_cvt_pk_bf16_f32 v129, v124, v125
	global_store_dwordx4 v[146:147], v[126:129], off
	global_load_dwordx4 v[170:173], v[142:143], off offset:256
	global_load_dwordx4 v[174:177], v[144:145], off offset:256
	s_waitcnt vmcnt(5)
	v_lshlrev_b32_e32 v178, 16, v154
	v_and_b32_e32 v154, 0xffff0000, v154
	v_lshlrev_b32_e32 v179, 16, v158
	v_and_b32_e32 v158, 0xffff0000, v158
	v_mul_f32_e32 v118, 0xbfb8aa3b, v118
	v_mul_f32_e32 v119, 0xbfb8aa3b, v119
	v_mul_f32_e32 v180, 0xbfb8aa3b, v179
	v_mul_f32_e32 v181, 0xbfb8aa3b, v158
	v_exp_f32_e32 v118, v118
	v_exp_f32_e32 v119, v119
	v_exp_f32_e32 v180, v180
	v_exp_f32_e32 v181, v181
	v_add_f32_e32 v118, 1.0, v118
	v_add_f32_e32 v119, 1.0, v119
	v_add_f32_e32 v180, 1.0, v180
	v_add_f32_e32 v181, 1.0, v181
	v_rcp_f32_e32 v118, v118
	v_rcp_f32_e32 v119, v119
	v_rcp_f32_e32 v180, v180
	v_rcp_f32_e32 v181, v181
	v_mul_f32_e32 v118, v118, v178
	v_mul_f32_e32 v119, v119, v154
	v_mul_f32_e32 v180, v180, v179
	v_mul_f32_e32 v181, v181, v158
	v_mul_f32_e32 v118, v118, v180
	v_mul_f32_e32 v119, v119, v181
	v_lshlrev_b32_e32 v178, 16, v155
	v_and_b32_e32 v155, 0xffff0000, v155
	v_lshlrev_b32_e32 v179, 16, v159
	v_and_b32_e32 v159, 0xffff0000, v159
	v_mul_f32_e32 v120, 0xbfb8aa3b, v120
	v_mul_f32_e32 v121, 0xbfb8aa3b, v121
	v_mul_f32_e32 v180, 0xbfb8aa3b, v179
	v_mul_f32_e32 v181, 0xbfb8aa3b, v159
	v_exp_f32_e32 v120, v120
	v_exp_f32_e32 v121, v121
	v_exp_f32_e32 v180, v180
	v_exp_f32_e32 v181, v181
	v_add_f32_e32 v120, 1.0, v120
	v_add_f32_e32 v121, 1.0, v121
	v_add_f32_e32 v180, 1.0, v180
	v_add_f32_e32 v181, 1.0, v181
	v_rcp_f32_e32 v120, v120
	v_rcp_f32_e32 v121, v121
	v_rcp_f32_e32 v180, v180
	v_rcp_f32_e32 v181, v181
	v_mul_f32_e32 v120, v120, v178
	v_mul_f32_e32 v121, v121, v155
	v_mul_f32_e32 v180, v180, v179
	v_mul_f32_e32 v181, v181, v159
	v_mul_f32_e32 v120, v120, v180
	v_mul_f32_e32 v121, v121, v181
	v_lshlrev_b32_e32 v178, 16, v156
	v_and_b32_e32 v156, 0xffff0000, v156
	v_lshlrev_b32_e32 v179, 16, v160
	v_and_b32_e32 v160, 0xffff0000, v160
	v_mul_f32_e32 v114, 0xbfb8aa3b, v114
	v_mul_f32_e32 v115, 0xbfb8aa3b, v115
	v_mul_f32_e32 v180, 0xbfb8aa3b, v179
	v_mul_f32_e32 v181, 0xbfb8aa3b, v160
	v_exp_f32_e32 v114, v114
	v_exp_f32_e32 v115, v115
	v_exp_f32_e32 v180, v180
	v_exp_f32_e32 v181, v181
	v_add_f32_e32 v114, 1.0, v114
	v_add_f32_e32 v115, 1.0, v115
	v_add_f32_e32 v180, 1.0, v180
	v_add_f32_e32 v181, 1.0, v181
	v_rcp_f32_e32 v114, v114
	v_rcp_f32_e32 v115, v115
	v_rcp_f32_e32 v180, v180
	v_rcp_f32_e32 v181, v181
	v_mul_f32_e32 v114, v114, v178
	v_mul_f32_e32 v115, v115, v156
	v_mul_f32_e32 v180, v180, v179
	v_mul_f32_e32 v181, v181, v160
	v_mul_f32_e32 v114, v114, v180
	v_mul_f32_e32 v115, v115, v181
	v_lshlrev_b32_e32 v178, 16, v157
	v_and_b32_e32 v157, 0xffff0000, v157
	v_lshlrev_b32_e32 v179, 16, v161
	v_and_b32_e32 v161, 0xffff0000, v161
	v_mul_f32_e32 v116, 0xbfb8aa3b, v116
	v_mul_f32_e32 v117, 0xbfb8aa3b, v117
	v_mul_f32_e32 v180, 0xbfb8aa3b, v179
	v_mul_f32_e32 v181, 0xbfb8aa3b, v161
	v_exp_f32_e32 v116, v116
	v_exp_f32_e32 v117, v117
	v_exp_f32_e32 v180, v180
	v_exp_f32_e32 v181, v181
	v_add_f32_e32 v116, 1.0, v116
	v_add_f32_e32 v117, 1.0, v117
	v_add_f32_e32 v180, 1.0, v180
	v_add_f32_e32 v181, 1.0, v181
	v_rcp_f32_e32 v116, v116
	v_rcp_f32_e32 v117, v117
	v_rcp_f32_e32 v180, v180
	v_rcp_f32_e32 v181, v181
	v_mul_f32_e32 v116, v116, v178
	v_mul_f32_e32 v117, v117, v157
	v_mul_f32_e32 v180, v180, v179
	v_mul_f32_e32 v181, v181, v161
	v_mul_f32_e32 v116, v116, v180
	v_mul_f32_e32 v117, v117, v181
	v_cvt_pk_bf16_f32 v118, v118, v119
	v_cvt_pk_bf16_f32 v119, v120, v121
	v_cvt_pk_bf16_f32 v120, v114, v115
	v_cvt_pk_bf16_f32 v121, v116, v117
	global_store_dwordx4 v[146:147], v[118:121], off offset:256
	s_mov_b64 s[58:59], 0x20000
	v_lshl_add_u64 v[146:147], v[146:147], 0, s[58:59]
	s_mov_b64 s[58:59], 0x8000
	v_lshl_add_u64 v[142:143], v[142:143], 0, s[58:59]
	s_mov_b64 s[58:59], 0x4000
	v_lshl_add_u64 v[144:145], v[144:145], 0, s[58:59]
	global_load_dwordx4 v[154:157], v[142:143], off
	global_load_dwordx4 v[158:161], v[144:145], off
	s_waitcnt vmcnt(6)
	v_lshlrev_b32_e32 v178, 16, v162
	v_and_b32_e32 v162, 0xffff0000, v162
	v_lshlrev_b32_e32 v179, 16, v166
	v_and_b32_e32 v166, 0xffff0000, v166
	v_mul_f32_e32 v110, 0xbfb8aa3b, v110
	v_mul_f32_e32 v111, 0xbfb8aa3b, v111
	v_mul_f32_e32 v180, 0xbfb8aa3b, v179
	v_mul_f32_e32 v181, 0xbfb8aa3b, v166
	v_exp_f32_e32 v110, v110
	v_exp_f32_e32 v111, v111
	v_exp_f32_e32 v180, v180
	v_exp_f32_e32 v181, v181
	v_add_f32_e32 v110, 1.0, v110
	v_add_f32_e32 v111, 1.0, v111
	v_add_f32_e32 v180, 1.0, v180
	v_add_f32_e32 v181, 1.0, v181
	v_rcp_f32_e32 v110, v110
	v_rcp_f32_e32 v111, v111
	v_rcp_f32_e32 v180, v180
	v_rcp_f32_e32 v181, v181
	v_mul_f32_e32 v110, v110, v178
	v_mul_f32_e32 v111, v111, v162
	v_mul_f32_e32 v180, v180, v179
	v_mul_f32_e32 v181, v181, v166
	v_mul_f32_e32 v110, v110, v180
	v_mul_f32_e32 v111, v111, v181
	v_lshlrev_b32_e32 v178, 16, v163
	v_and_b32_e32 v163, 0xffff0000, v163
	v_lshlrev_b32_e32 v179, 16, v167
	v_and_b32_e32 v167, 0xffff0000, v167
	v_mul_f32_e32 v112, 0xbfb8aa3b, v112
	v_mul_f32_e32 v113, 0xbfb8aa3b, v113
	v_mul_f32_e32 v180, 0xbfb8aa3b, v179
	v_mul_f32_e32 v181, 0xbfb8aa3b, v167
	v_exp_f32_e32 v112, v112
	v_exp_f32_e32 v113, v113
	v_exp_f32_e32 v180, v180
	v_exp_f32_e32 v181, v181
	v_add_f32_e32 v112, 1.0, v112
	v_add_f32_e32 v113, 1.0, v113
	v_add_f32_e32 v180, 1.0, v180
	v_add_f32_e32 v181, 1.0, v181
	v_rcp_f32_e32 v112, v112
	v_rcp_f32_e32 v113, v113
	v_rcp_f32_e32 v180, v180
	v_rcp_f32_e32 v181, v181
	v_mul_f32_e32 v112, v112, v178
	v_mul_f32_e32 v113, v113, v163
	v_mul_f32_e32 v180, v180, v179
	v_mul_f32_e32 v181, v181, v167
	v_mul_f32_e32 v112, v112, v180
	v_mul_f32_e32 v113, v113, v181
	v_lshlrev_b32_e32 v178, 16, v164
	v_and_b32_e32 v164, 0xffff0000, v164
	v_lshlrev_b32_e32 v179, 16, v168
	v_and_b32_e32 v168, 0xffff0000, v168
	v_mul_f32_e32 v106, 0xbfb8aa3b, v106
	v_mul_f32_e32 v107, 0xbfb8aa3b, v107
	v_mul_f32_e32 v180, 0xbfb8aa3b, v179
	v_mul_f32_e32 v181, 0xbfb8aa3b, v168
	v_exp_f32_e32 v106, v106
	v_exp_f32_e32 v107, v107
	v_exp_f32_e32 v180, v180
	v_exp_f32_e32 v181, v181
	v_add_f32_e32 v106, 1.0, v106
	v_add_f32_e32 v107, 1.0, v107
	v_add_f32_e32 v180, 1.0, v180
	v_add_f32_e32 v181, 1.0, v181
	v_rcp_f32_e32 v106, v106
	v_rcp_f32_e32 v107, v107
	v_rcp_f32_e32 v180, v180
	v_rcp_f32_e32 v181, v181
	v_mul_f32_e32 v106, v106, v178
	v_mul_f32_e32 v107, v107, v164
	v_mul_f32_e32 v180, v180, v179
	v_mul_f32_e32 v181, v181, v168
	v_mul_f32_e32 v106, v106, v180
	v_mul_f32_e32 v107, v107, v181
	v_lshlrev_b32_e32 v178, 16, v165
	v_and_b32_e32 v165, 0xffff0000, v165
	v_lshlrev_b32_e32 v179, 16, v169
	v_and_b32_e32 v169, 0xffff0000, v169
	v_mul_f32_e32 v108, 0xbfb8aa3b, v108
	v_mul_f32_e32 v109, 0xbfb8aa3b, v109
	v_mul_f32_e32 v180, 0xbfb8aa3b, v179
	v_mul_f32_e32 v181, 0xbfb8aa3b, v169
	v_exp_f32_e32 v108, v108
	v_exp_f32_e32 v109, v109
	v_exp_f32_e32 v180, v180
	v_exp_f32_e32 v181, v181
	v_add_f32_e32 v108, 1.0, v108
	v_add_f32_e32 v109, 1.0, v109
	v_add_f32_e32 v180, 1.0, v180
	v_add_f32_e32 v181, 1.0, v181
	v_rcp_f32_e32 v108, v108
	v_rcp_f32_e32 v109, v109
	v_rcp_f32_e32 v180, v180
	v_rcp_f32_e32 v181, v181
	v_mul_f32_e32 v108, v108, v178
	v_mul_f32_e32 v109, v109, v165
	v_mul_f32_e32 v180, v180, v179
	v_mul_f32_e32 v181, v181, v169
	v_mul_f32_e32 v108, v108, v180
	v_mul_f32_e32 v109, v109, v181
	v_cvt_pk_bf16_f32 v110, v110, v111
	v_cvt_pk_bf16_f32 v111, v112, v113
	v_cvt_pk_bf16_f32 v112, v106, v107
	v_cvt_pk_bf16_f32 v113, v108, v109
	global_store_dwordx4 v[146:147], v[110:113], off
	global_load_dwordx4 v[162:165], v[142:143], off offset:256
	global_load_dwordx4 v[166:169], v[144:145], off offset:256
	s_waitcnt vmcnt(6)
	v_lshlrev_b32_e32 v178, 16, v170
	v_and_b32_e32 v170, 0xffff0000, v170
	v_lshlrev_b32_e32 v179, 16, v174
	v_and_b32_e32 v174, 0xffff0000, v174
	v_mul_f32_e32 v102, 0xbfb8aa3b, v102
	v_mul_f32_e32 v103, 0xbfb8aa3b, v103
	v_mul_f32_e32 v180, 0xbfb8aa3b, v179
	v_mul_f32_e32 v181, 0xbfb8aa3b, v174
	v_exp_f32_e32 v102, v102
	v_exp_f32_e32 v103, v103
	v_exp_f32_e32 v180, v180
	v_exp_f32_e32 v181, v181
	v_add_f32_e32 v102, 1.0, v102
	v_add_f32_e32 v103, 1.0, v103
	v_add_f32_e32 v180, 1.0, v180
	v_add_f32_e32 v181, 1.0, v181
	v_rcp_f32_e32 v102, v102
	v_rcp_f32_e32 v103, v103
	v_rcp_f32_e32 v180, v180
	v_rcp_f32_e32 v181, v181
	v_mul_f32_e32 v102, v102, v178
	v_mul_f32_e32 v103, v103, v170
	v_mul_f32_e32 v180, v180, v179
	v_mul_f32_e32 v181, v181, v174
	v_mul_f32_e32 v102, v102, v180
	v_mul_f32_e32 v103, v103, v181
	v_lshlrev_b32_e32 v178, 16, v171
	v_and_b32_e32 v171, 0xffff0000, v171
	v_lshlrev_b32_e32 v179, 16, v175
	v_and_b32_e32 v175, 0xffff0000, v175
	v_mul_f32_e32 v104, 0xbfb8aa3b, v104
	v_mul_f32_e32 v105, 0xbfb8aa3b, v105
	v_mul_f32_e32 v180, 0xbfb8aa3b, v179
	v_mul_f32_e32 v181, 0xbfb8aa3b, v175
	v_exp_f32_e32 v104, v104
	v_exp_f32_e32 v105, v105
	v_exp_f32_e32 v180, v180
	v_exp_f32_e32 v181, v181
	v_add_f32_e32 v104, 1.0, v104
	v_add_f32_e32 v105, 1.0, v105
	v_add_f32_e32 v180, 1.0, v180
	v_add_f32_e32 v181, 1.0, v181
	v_rcp_f32_e32 v104, v104
	v_rcp_f32_e32 v105, v105
	v_rcp_f32_e32 v180, v180
	v_rcp_f32_e32 v181, v181
	v_mul_f32_e32 v104, v104, v178
	v_mul_f32_e32 v105, v105, v171
	v_mul_f32_e32 v180, v180, v179
	v_mul_f32_e32 v181, v181, v175
	v_mul_f32_e32 v104, v104, v180
	v_mul_f32_e32 v105, v105, v181
	v_lshlrev_b32_e32 v178, 16, v172
	v_and_b32_e32 v172, 0xffff0000, v172
	v_lshlrev_b32_e32 v179, 16, v176
	v_and_b32_e32 v176, 0xffff0000, v176
	v_mul_f32_e32 v98, 0xbfb8aa3b, v98
	v_mul_f32_e32 v99, 0xbfb8aa3b, v99
	v_mul_f32_e32 v180, 0xbfb8aa3b, v179
	v_mul_f32_e32 v181, 0xbfb8aa3b, v176
	v_exp_f32_e32 v98, v98
	v_exp_f32_e32 v99, v99
	v_exp_f32_e32 v180, v180
	v_exp_f32_e32 v181, v181
	v_add_f32_e32 v98, 1.0, v98
	v_add_f32_e32 v99, 1.0, v99
	v_add_f32_e32 v180, 1.0, v180
	v_add_f32_e32 v181, 1.0, v181
	v_rcp_f32_e32 v98, v98
	v_rcp_f32_e32 v99, v99
	v_rcp_f32_e32 v180, v180
	v_rcp_f32_e32 v181, v181
	v_mul_f32_e32 v98, v98, v178
	v_mul_f32_e32 v99, v99, v172
	v_mul_f32_e32 v180, v180, v179
	v_mul_f32_e32 v181, v181, v176
	v_mul_f32_e32 v98, v98, v180
	v_mul_f32_e32 v99, v99, v181
	v_lshlrev_b32_e32 v178, 16, v173
	v_and_b32_e32 v173, 0xffff0000, v173
	v_lshlrev_b32_e32 v179, 16, v177
	v_and_b32_e32 v177, 0xffff0000, v177
	v_mul_f32_e32 v100, 0xbfb8aa3b, v100
	v_mul_f32_e32 v101, 0xbfb8aa3b, v101
	v_mul_f32_e32 v180, 0xbfb8aa3b, v179
	v_mul_f32_e32 v181, 0xbfb8aa3b, v177
	v_exp_f32_e32 v100, v100
	v_exp_f32_e32 v101, v101
	v_exp_f32_e32 v180, v180
	v_exp_f32_e32 v181, v181
	v_add_f32_e32 v100, 1.0, v100
	v_add_f32_e32 v101, 1.0, v101
	v_add_f32_e32 v180, 1.0, v180
	v_add_f32_e32 v181, 1.0, v181
	v_rcp_f32_e32 v100, v100
	v_rcp_f32_e32 v101, v101
	v_rcp_f32_e32 v180, v180
	v_rcp_f32_e32 v181, v181
	v_mul_f32_e32 v100, v100, v178
	v_mul_f32_e32 v101, v101, v173
	v_mul_f32_e32 v180, v180, v179
	v_mul_f32_e32 v181, v181, v177
	v_mul_f32_e32 v100, v100, v180
	v_mul_f32_e32 v101, v101, v181
	v_cvt_pk_bf16_f32 v102, v102, v103
	v_cvt_pk_bf16_f32 v103, v104, v105
	v_cvt_pk_bf16_f32 v104, v98, v99
	v_cvt_pk_bf16_f32 v105, v100, v101
	global_store_dwordx4 v[146:147], v[102:105], off offset:256
	s_mov_b64 s[58:59], 0x20000
	v_lshl_add_u64 v[146:147], v[146:147], 0, s[58:59]
	s_mov_b64 s[58:59], 0x8000
	v_lshl_add_u64 v[142:143], v[142:143], 0, s[58:59]
	s_mov_b64 s[58:59], 0x4000
	v_lshl_add_u64 v[144:145], v[144:145], 0, s[58:59]
	global_load_dwordx4 v[170:173], v[142:143], off
	global_load_dwordx4 v[174:177], v[144:145], off
	s_waitcnt vmcnt(6)
	v_lshlrev_b32_e32 v178, 16, v154
	v_and_b32_e32 v154, 0xffff0000, v154
	v_lshlrev_b32_e32 v179, 16, v158
	v_and_b32_e32 v158, 0xffff0000, v158
	v_mul_f32_e32 v94, 0xbfb8aa3b, v94
	v_mul_f32_e32 v95, 0xbfb8aa3b, v95
	v_mul_f32_e32 v180, 0xbfb8aa3b, v179
	v_mul_f32_e32 v181, 0xbfb8aa3b, v158
	v_exp_f32_e32 v94, v94
	v_exp_f32_e32 v95, v95
	v_exp_f32_e32 v180, v180
	v_exp_f32_e32 v181, v181
	v_add_f32_e32 v94, 1.0, v94
	v_add_f32_e32 v95, 1.0, v95
	v_add_f32_e32 v180, 1.0, v180
	v_add_f32_e32 v181, 1.0, v181
	v_rcp_f32_e32 v94, v94
	v_rcp_f32_e32 v95, v95
	v_rcp_f32_e32 v180, v180
	v_rcp_f32_e32 v181, v181
	v_mul_f32_e32 v94, v94, v178
	v_mul_f32_e32 v95, v95, v154
	v_mul_f32_e32 v180, v180, v179
	v_mul_f32_e32 v181, v181, v158
	v_mul_f32_e32 v94, v94, v180
	v_mul_f32_e32 v95, v95, v181
	v_lshlrev_b32_e32 v178, 16, v155
	v_and_b32_e32 v155, 0xffff0000, v155
	v_lshlrev_b32_e32 v179, 16, v159
	v_and_b32_e32 v159, 0xffff0000, v159
	v_mul_f32_e32 v96, 0xbfb8aa3b, v96
	v_mul_f32_e32 v97, 0xbfb8aa3b, v97
	v_mul_f32_e32 v180, 0xbfb8aa3b, v179
	v_mul_f32_e32 v181, 0xbfb8aa3b, v159
	v_exp_f32_e32 v96, v96
	v_exp_f32_e32 v97, v97
	v_exp_f32_e32 v180, v180
	v_exp_f32_e32 v181, v181
	v_add_f32_e32 v96, 1.0, v96
	v_add_f32_e32 v97, 1.0, v97
	v_add_f32_e32 v180, 1.0, v180
	v_add_f32_e32 v181, 1.0, v181
	v_rcp_f32_e32 v96, v96
	v_rcp_f32_e32 v97, v97
	v_rcp_f32_e32 v180, v180
	v_rcp_f32_e32 v181, v181
	v_mul_f32_e32 v96, v96, v178
	v_mul_f32_e32 v97, v97, v155
	v_mul_f32_e32 v180, v180, v179
	v_mul_f32_e32 v181, v181, v159
	v_mul_f32_e32 v96, v96, v180
	v_mul_f32_e32 v97, v97, v181
	v_lshlrev_b32_e32 v178, 16, v156
	v_and_b32_e32 v156, 0xffff0000, v156
	v_lshlrev_b32_e32 v179, 16, v160
	v_and_b32_e32 v160, 0xffff0000, v160
	v_mul_f32_e32 v90, 0xbfb8aa3b, v90
	v_mul_f32_e32 v91, 0xbfb8aa3b, v91
	v_mul_f32_e32 v180, 0xbfb8aa3b, v179
	v_mul_f32_e32 v181, 0xbfb8aa3b, v160
	v_exp_f32_e32 v90, v90
	v_exp_f32_e32 v91, v91
	v_exp_f32_e32 v180, v180
	v_exp_f32_e32 v181, v181
	v_add_f32_e32 v90, 1.0, v90
	v_add_f32_e32 v91, 1.0, v91
	v_add_f32_e32 v180, 1.0, v180
	v_add_f32_e32 v181, 1.0, v181
	v_rcp_f32_e32 v90, v90
	v_rcp_f32_e32 v91, v91
	v_rcp_f32_e32 v180, v180
	v_rcp_f32_e32 v181, v181
	v_mul_f32_e32 v90, v90, v178
	v_mul_f32_e32 v91, v91, v156
	v_mul_f32_e32 v180, v180, v179
	v_mul_f32_e32 v181, v181, v160
	v_mul_f32_e32 v90, v90, v180
	v_mul_f32_e32 v91, v91, v181
	v_lshlrev_b32_e32 v178, 16, v157
	v_and_b32_e32 v157, 0xffff0000, v157
	v_lshlrev_b32_e32 v179, 16, v161
	v_and_b32_e32 v161, 0xffff0000, v161
	v_mul_f32_e32 v92, 0xbfb8aa3b, v92
	v_mul_f32_e32 v93, 0xbfb8aa3b, v93
	v_mul_f32_e32 v180, 0xbfb8aa3b, v179
	v_mul_f32_e32 v181, 0xbfb8aa3b, v161
	v_exp_f32_e32 v92, v92
	v_exp_f32_e32 v93, v93
	v_exp_f32_e32 v180, v180
	v_exp_f32_e32 v181, v181
	v_add_f32_e32 v92, 1.0, v92
	v_add_f32_e32 v93, 1.0, v93
	v_add_f32_e32 v180, 1.0, v180
	v_add_f32_e32 v181, 1.0, v181
	v_rcp_f32_e32 v92, v92
	v_rcp_f32_e32 v93, v93
	v_rcp_f32_e32 v180, v180
	v_rcp_f32_e32 v181, v181
	v_mul_f32_e32 v92, v92, v178
	v_mul_f32_e32 v93, v93, v157
	v_mul_f32_e32 v180, v180, v179
	v_mul_f32_e32 v181, v181, v161
	v_mul_f32_e32 v92, v92, v180
	v_mul_f32_e32 v93, v93, v181
	v_cvt_pk_bf16_f32 v94, v94, v95
	v_cvt_pk_bf16_f32 v95, v96, v97
	v_cvt_pk_bf16_f32 v96, v90, v91
	v_cvt_pk_bf16_f32 v97, v92, v93
	global_store_dwordx4 v[146:147], v[94:97], off
	global_load_dwordx4 v[154:157], v[142:143], off offset:256
	global_load_dwordx4 v[158:161], v[144:145], off offset:256
	s_waitcnt vmcnt(6)
	v_lshlrev_b32_e32 v178, 16, v162
	v_and_b32_e32 v162, 0xffff0000, v162
	v_lshlrev_b32_e32 v179, 16, v166
	v_and_b32_e32 v166, 0xffff0000, v166
	v_mul_f32_e32 v86, 0xbfb8aa3b, v86
	v_mul_f32_e32 v87, 0xbfb8aa3b, v87
	v_mul_f32_e32 v180, 0xbfb8aa3b, v179
	v_mul_f32_e32 v181, 0xbfb8aa3b, v166
	v_exp_f32_e32 v86, v86
	v_exp_f32_e32 v87, v87
	v_exp_f32_e32 v180, v180
	v_exp_f32_e32 v181, v181
	v_add_f32_e32 v86, 1.0, v86
	v_add_f32_e32 v87, 1.0, v87
	v_add_f32_e32 v180, 1.0, v180
	v_add_f32_e32 v181, 1.0, v181
	v_rcp_f32_e32 v86, v86
	v_rcp_f32_e32 v87, v87
	v_rcp_f32_e32 v180, v180
	v_rcp_f32_e32 v181, v181
	v_mul_f32_e32 v86, v86, v178
	v_mul_f32_e32 v87, v87, v162
	v_mul_f32_e32 v180, v180, v179
	v_mul_f32_e32 v181, v181, v166
	v_mul_f32_e32 v86, v86, v180
	v_mul_f32_e32 v87, v87, v181
	v_lshlrev_b32_e32 v178, 16, v163
	v_and_b32_e32 v163, 0xffff0000, v163
	v_lshlrev_b32_e32 v179, 16, v167
	v_and_b32_e32 v167, 0xffff0000, v167
	v_mul_f32_e32 v88, 0xbfb8aa3b, v88
	v_mul_f32_e32 v89, 0xbfb8aa3b, v89
	v_mul_f32_e32 v180, 0xbfb8aa3b, v179
	v_mul_f32_e32 v181, 0xbfb8aa3b, v167
	v_exp_f32_e32 v88, v88
	v_exp_f32_e32 v89, v89
	v_exp_f32_e32 v180, v180
	v_exp_f32_e32 v181, v181
	v_add_f32_e32 v88, 1.0, v88
	v_add_f32_e32 v89, 1.0, v89
	v_add_f32_e32 v180, 1.0, v180
	v_add_f32_e32 v181, 1.0, v181
	v_rcp_f32_e32 v88, v88
	v_rcp_f32_e32 v89, v89
	v_rcp_f32_e32 v180, v180
	v_rcp_f32_e32 v181, v181
	v_mul_f32_e32 v88, v88, v178
	v_mul_f32_e32 v89, v89, v163
	v_mul_f32_e32 v180, v180, v179
	v_mul_f32_e32 v181, v181, v167
	v_mul_f32_e32 v88, v88, v180
	v_mul_f32_e32 v89, v89, v181
	v_lshlrev_b32_e32 v178, 16, v164
	v_and_b32_e32 v164, 0xffff0000, v164
	v_lshlrev_b32_e32 v179, 16, v168
	v_and_b32_e32 v168, 0xffff0000, v168
	v_mul_f32_e32 v82, 0xbfb8aa3b, v82
	v_mul_f32_e32 v83, 0xbfb8aa3b, v83
	v_mul_f32_e32 v180, 0xbfb8aa3b, v179
	v_mul_f32_e32 v181, 0xbfb8aa3b, v168
	v_exp_f32_e32 v82, v82
	v_exp_f32_e32 v83, v83
	v_exp_f32_e32 v180, v180
	v_exp_f32_e32 v181, v181
	v_add_f32_e32 v82, 1.0, v82
	v_add_f32_e32 v83, 1.0, v83
	v_add_f32_e32 v180, 1.0, v180
	v_add_f32_e32 v181, 1.0, v181
	v_rcp_f32_e32 v82, v82
	v_rcp_f32_e32 v83, v83
	v_rcp_f32_e32 v180, v180
	v_rcp_f32_e32 v181, v181
	v_mul_f32_e32 v82, v82, v178
	v_mul_f32_e32 v83, v83, v164
	v_mul_f32_e32 v180, v180, v179
	v_mul_f32_e32 v181, v181, v168
	v_mul_f32_e32 v82, v82, v180
	v_mul_f32_e32 v83, v83, v181
	v_lshlrev_b32_e32 v178, 16, v165
	v_and_b32_e32 v165, 0xffff0000, v165
	v_lshlrev_b32_e32 v179, 16, v169
	v_and_b32_e32 v169, 0xffff0000, v169
	v_mul_f32_e32 v84, 0xbfb8aa3b, v84
	v_mul_f32_e32 v85, 0xbfb8aa3b, v85
	v_mul_f32_e32 v180, 0xbfb8aa3b, v179
	v_mul_f32_e32 v181, 0xbfb8aa3b, v169
	v_exp_f32_e32 v84, v84
	v_exp_f32_e32 v85, v85
	v_exp_f32_e32 v180, v180
	v_exp_f32_e32 v181, v181
	v_add_f32_e32 v84, 1.0, v84
	v_add_f32_e32 v85, 1.0, v85
	v_add_f32_e32 v180, 1.0, v180
	v_add_f32_e32 v181, 1.0, v181
	v_rcp_f32_e32 v84, v84
	v_rcp_f32_e32 v85, v85
	v_rcp_f32_e32 v180, v180
	v_rcp_f32_e32 v181, v181
	v_mul_f32_e32 v84, v84, v178
	v_mul_f32_e32 v85, v85, v165
	v_mul_f32_e32 v180, v180, v179
	v_mul_f32_e32 v181, v181, v169
	v_mul_f32_e32 v84, v84, v180
	v_mul_f32_e32 v85, v85, v181
	v_cvt_pk_bf16_f32 v86, v86, v87
	v_cvt_pk_bf16_f32 v87, v88, v89
	v_cvt_pk_bf16_f32 v88, v82, v83
	v_cvt_pk_bf16_f32 v89, v84, v85
	global_store_dwordx4 v[146:147], v[86:89], off offset:256
	s_mov_b64 s[58:59], 0x20000
	v_lshl_add_u64 v[146:147], v[146:147], 0, s[58:59]
	s_mov_b64 s[58:59], 0x28000
	v_lshl_add_u64 v[142:143], v[142:143], 0, s[58:59]
	s_mov_b64 s[58:59], 0x14000
	v_lshl_add_u64 v[144:145], v[144:145], 0, s[58:59]
	global_load_dwordx4 v[162:165], v[142:143], off
	global_load_dwordx4 v[166:169], v[144:145], off
	s_waitcnt vmcnt(6)
	v_lshlrev_b32_e32 v178, 16, v170
	v_and_b32_e32 v170, 0xffff0000, v170
	v_lshlrev_b32_e32 v179, 16, v174
	v_and_b32_e32 v174, 0xffff0000, v174
	v_mul_f32_e32 v78, 0xbfb8aa3b, v78
	v_mul_f32_e32 v79, 0xbfb8aa3b, v79
	v_mul_f32_e32 v180, 0xbfb8aa3b, v179
	v_mul_f32_e32 v181, 0xbfb8aa3b, v174
	v_exp_f32_e32 v78, v78
	v_exp_f32_e32 v79, v79
	v_exp_f32_e32 v180, v180
	v_exp_f32_e32 v181, v181
	v_add_f32_e32 v78, 1.0, v78
	v_add_f32_e32 v79, 1.0, v79
	v_add_f32_e32 v180, 1.0, v180
	v_add_f32_e32 v181, 1.0, v181
	v_rcp_f32_e32 v78, v78
	v_rcp_f32_e32 v79, v79
	v_rcp_f32_e32 v180, v180
	v_rcp_f32_e32 v181, v181
	v_mul_f32_e32 v78, v78, v178
	v_mul_f32_e32 v79, v79, v170
	v_mul_f32_e32 v180, v180, v179
	v_mul_f32_e32 v181, v181, v174
	v_mul_f32_e32 v78, v78, v180
	v_mul_f32_e32 v79, v79, v181
	v_lshlrev_b32_e32 v178, 16, v171
	v_and_b32_e32 v171, 0xffff0000, v171
	v_lshlrev_b32_e32 v179, 16, v175
	v_and_b32_e32 v175, 0xffff0000, v175
	v_mul_f32_e32 v80, 0xbfb8aa3b, v80
	v_mul_f32_e32 v81, 0xbfb8aa3b, v81
	v_mul_f32_e32 v180, 0xbfb8aa3b, v179
	v_mul_f32_e32 v181, 0xbfb8aa3b, v175
	v_exp_f32_e32 v80, v80
	v_exp_f32_e32 v81, v81
	v_exp_f32_e32 v180, v180
	v_exp_f32_e32 v181, v181
	v_add_f32_e32 v80, 1.0, v80
	v_add_f32_e32 v81, 1.0, v81
	v_add_f32_e32 v180, 1.0, v180
	v_add_f32_e32 v181, 1.0, v181
	v_rcp_f32_e32 v80, v80
	v_rcp_f32_e32 v81, v81
	v_rcp_f32_e32 v180, v180
	v_rcp_f32_e32 v181, v181
	v_mul_f32_e32 v80, v80, v178
	v_mul_f32_e32 v81, v81, v171
	v_mul_f32_e32 v180, v180, v179
	v_mul_f32_e32 v181, v181, v175
	v_mul_f32_e32 v80, v80, v180
	v_mul_f32_e32 v81, v81, v181
	v_lshlrev_b32_e32 v178, 16, v172
	v_and_b32_e32 v172, 0xffff0000, v172
	v_lshlrev_b32_e32 v179, 16, v176
	v_and_b32_e32 v176, 0xffff0000, v176
	v_mul_f32_e32 v74, 0xbfb8aa3b, v74
	v_mul_f32_e32 v75, 0xbfb8aa3b, v75
	v_mul_f32_e32 v180, 0xbfb8aa3b, v179
	v_mul_f32_e32 v181, 0xbfb8aa3b, v176
	v_exp_f32_e32 v74, v74
	v_exp_f32_e32 v75, v75
	v_exp_f32_e32 v180, v180
	v_exp_f32_e32 v181, v181
	v_add_f32_e32 v74, 1.0, v74
	v_add_f32_e32 v75, 1.0, v75
	v_add_f32_e32 v180, 1.0, v180
	v_add_f32_e32 v181, 1.0, v181
	v_rcp_f32_e32 v74, v74
	v_rcp_f32_e32 v75, v75
	v_rcp_f32_e32 v180, v180
	v_rcp_f32_e32 v181, v181
	v_mul_f32_e32 v74, v74, v178
	v_mul_f32_e32 v75, v75, v172
	v_mul_f32_e32 v180, v180, v179
	v_mul_f32_e32 v181, v181, v176
	v_mul_f32_e32 v74, v74, v180
	v_mul_f32_e32 v75, v75, v181
	v_lshlrev_b32_e32 v178, 16, v173
	v_and_b32_e32 v173, 0xffff0000, v173
	v_lshlrev_b32_e32 v179, 16, v177
	v_and_b32_e32 v177, 0xffff0000, v177
	v_mul_f32_e32 v76, 0xbfb8aa3b, v76
	v_mul_f32_e32 v77, 0xbfb8aa3b, v77
	v_mul_f32_e32 v180, 0xbfb8aa3b, v179
	v_mul_f32_e32 v181, 0xbfb8aa3b, v177
	v_exp_f32_e32 v76, v76
	v_exp_f32_e32 v77, v77
	v_exp_f32_e32 v180, v180
	v_exp_f32_e32 v181, v181
	v_add_f32_e32 v76, 1.0, v76
	v_add_f32_e32 v77, 1.0, v77
	v_add_f32_e32 v180, 1.0, v180
	v_add_f32_e32 v181, 1.0, v181
	v_rcp_f32_e32 v76, v76
	v_rcp_f32_e32 v77, v77
	v_rcp_f32_e32 v180, v180
	v_rcp_f32_e32 v181, v181
	v_mul_f32_e32 v76, v76, v178
	v_mul_f32_e32 v77, v77, v173
	v_mul_f32_e32 v180, v180, v179
	v_mul_f32_e32 v181, v181, v177
	v_mul_f32_e32 v76, v76, v180
	v_mul_f32_e32 v77, v77, v181
	v_cvt_pk_bf16_f32 v78, v78, v79
	v_cvt_pk_bf16_f32 v79, v80, v81
	v_cvt_pk_bf16_f32 v80, v74, v75
	v_cvt_pk_bf16_f32 v81, v76, v77
	global_store_dwordx4 v[146:147], v[78:81], off
	global_load_dwordx4 v[170:173], v[142:143], off offset:256
	global_load_dwordx4 v[174:177], v[144:145], off offset:256
	s_waitcnt vmcnt(6)
	v_lshlrev_b32_e32 v178, 16, v154
	v_and_b32_e32 v154, 0xffff0000, v154
	v_lshlrev_b32_e32 v179, 16, v158
	v_and_b32_e32 v158, 0xffff0000, v158
	v_mul_f32_e32 v70, 0xbfb8aa3b, v70
	v_mul_f32_e32 v71, 0xbfb8aa3b, v71
	v_mul_f32_e32 v180, 0xbfb8aa3b, v179
	v_mul_f32_e32 v181, 0xbfb8aa3b, v158
	v_exp_f32_e32 v70, v70
	v_exp_f32_e32 v71, v71
	v_exp_f32_e32 v180, v180
	v_exp_f32_e32 v181, v181
	v_add_f32_e32 v70, 1.0, v70
	v_add_f32_e32 v71, 1.0, v71
	v_add_f32_e32 v180, 1.0, v180
	v_add_f32_e32 v181, 1.0, v181
	v_rcp_f32_e32 v70, v70
	v_rcp_f32_e32 v71, v71
	v_rcp_f32_e32 v180, v180
	v_rcp_f32_e32 v181, v181
	v_mul_f32_e32 v70, v70, v178
	v_mul_f32_e32 v71, v71, v154
	v_mul_f32_e32 v180, v180, v179
	v_mul_f32_e32 v181, v181, v158
	v_mul_f32_e32 v70, v70, v180
	v_mul_f32_e32 v71, v71, v181
	v_lshlrev_b32_e32 v178, 16, v155
	v_and_b32_e32 v155, 0xffff0000, v155
	v_lshlrev_b32_e32 v179, 16, v159
	v_and_b32_e32 v159, 0xffff0000, v159
	v_mul_f32_e32 v72, 0xbfb8aa3b, v72
	v_mul_f32_e32 v73, 0xbfb8aa3b, v73
	v_mul_f32_e32 v180, 0xbfb8aa3b, v179
	v_mul_f32_e32 v181, 0xbfb8aa3b, v159
	v_exp_f32_e32 v72, v72
	v_exp_f32_e32 v73, v73
	v_exp_f32_e32 v180, v180
	v_exp_f32_e32 v181, v181
	v_add_f32_e32 v72, 1.0, v72
	v_add_f32_e32 v73, 1.0, v73
	v_add_f32_e32 v180, 1.0, v180
	v_add_f32_e32 v181, 1.0, v181
	v_rcp_f32_e32 v72, v72
	v_rcp_f32_e32 v73, v73
	v_rcp_f32_e32 v180, v180
	v_rcp_f32_e32 v181, v181
	v_mul_f32_e32 v72, v72, v178
	v_mul_f32_e32 v73, v73, v155
	v_mul_f32_e32 v180, v180, v179
	v_mul_f32_e32 v181, v181, v159
	v_mul_f32_e32 v72, v72, v180
	v_mul_f32_e32 v73, v73, v181
	v_lshlrev_b32_e32 v178, 16, v156
	v_and_b32_e32 v156, 0xffff0000, v156
	v_lshlrev_b32_e32 v179, 16, v160
	v_and_b32_e32 v160, 0xffff0000, v160
	v_mul_f32_e32 v66, 0xbfb8aa3b, v66
	v_mul_f32_e32 v67, 0xbfb8aa3b, v67
	v_mul_f32_e32 v180, 0xbfb8aa3b, v179
	v_mul_f32_e32 v181, 0xbfb8aa3b, v160
	v_exp_f32_e32 v66, v66
	v_exp_f32_e32 v67, v67
	v_exp_f32_e32 v180, v180
	v_exp_f32_e32 v181, v181
	v_add_f32_e32 v66, 1.0, v66
	v_add_f32_e32 v67, 1.0, v67
	v_add_f32_e32 v180, 1.0, v180
	v_add_f32_e32 v181, 1.0, v181
	v_rcp_f32_e32 v66, v66
	v_rcp_f32_e32 v67, v67
	v_rcp_f32_e32 v180, v180
	v_rcp_f32_e32 v181, v181
	v_mul_f32_e32 v66, v66, v178
	v_mul_f32_e32 v67, v67, v156
	v_mul_f32_e32 v180, v180, v179
	v_mul_f32_e32 v181, v181, v160
	v_mul_f32_e32 v66, v66, v180
	v_mul_f32_e32 v67, v67, v181
	v_lshlrev_b32_e32 v178, 16, v157
	v_and_b32_e32 v157, 0xffff0000, v157
	v_lshlrev_b32_e32 v179, 16, v161
	v_and_b32_e32 v161, 0xffff0000, v161
	v_mul_f32_e32 v68, 0xbfb8aa3b, v68
	v_mul_f32_e32 v69, 0xbfb8aa3b, v69
	v_mul_f32_e32 v180, 0xbfb8aa3b, v179
	v_mul_f32_e32 v181, 0xbfb8aa3b, v161
	v_exp_f32_e32 v68, v68
	v_exp_f32_e32 v69, v69
	v_exp_f32_e32 v180, v180
	v_exp_f32_e32 v181, v181
	v_add_f32_e32 v68, 1.0, v68
	v_add_f32_e32 v69, 1.0, v69
	v_add_f32_e32 v180, 1.0, v180
	v_add_f32_e32 v181, 1.0, v181
	v_rcp_f32_e32 v68, v68
	v_rcp_f32_e32 v69, v69
	v_rcp_f32_e32 v180, v180
	v_rcp_f32_e32 v181, v181
	v_mul_f32_e32 v68, v68, v178
	v_mul_f32_e32 v69, v69, v157
	v_mul_f32_e32 v180, v180, v179
	v_mul_f32_e32 v181, v181, v161
	v_mul_f32_e32 v68, v68, v180
	v_mul_f32_e32 v69, v69, v181
	v_cvt_pk_bf16_f32 v70, v70, v71
	v_cvt_pk_bf16_f32 v71, v72, v73
	v_cvt_pk_bf16_f32 v72, v66, v67
	v_cvt_pk_bf16_f32 v73, v68, v69
	global_store_dwordx4 v[146:147], v[70:73], off offset:256
	s_mov_b64 s[58:59], 0xa0000
	v_lshl_add_u64 v[146:147], v[146:147], 0, s[58:59]
	s_mov_b64 s[58:59], 0x8000
	v_lshl_add_u64 v[142:143], v[142:143], 0, s[58:59]
	s_mov_b64 s[58:59], 0x4000
	v_lshl_add_u64 v[144:145], v[144:145], 0, s[58:59]
	global_load_dwordx4 v[154:157], v[142:143], off
	global_load_dwordx4 v[158:161], v[144:145], off
	s_waitcnt vmcnt(6)
	v_lshlrev_b32_e32 v178, 16, v162
	v_and_b32_e32 v162, 0xffff0000, v162
	v_lshlrev_b32_e32 v179, 16, v166
	v_and_b32_e32 v166, 0xffff0000, v166
	v_mul_f32_e32 v62, 0xbfb8aa3b, v62
	v_mul_f32_e32 v63, 0xbfb8aa3b, v63
	v_mul_f32_e32 v180, 0xbfb8aa3b, v179
	v_mul_f32_e32 v181, 0xbfb8aa3b, v166
	v_exp_f32_e32 v62, v62
	v_exp_f32_e32 v63, v63
	v_exp_f32_e32 v180, v180
	v_exp_f32_e32 v181, v181
	v_add_f32_e32 v62, 1.0, v62
	v_add_f32_e32 v63, 1.0, v63
	v_add_f32_e32 v180, 1.0, v180
	v_add_f32_e32 v181, 1.0, v181
	v_rcp_f32_e32 v62, v62
	v_rcp_f32_e32 v63, v63
	v_rcp_f32_e32 v180, v180
	v_rcp_f32_e32 v181, v181
	v_mul_f32_e32 v62, v62, v178
	v_mul_f32_e32 v63, v63, v162
	v_mul_f32_e32 v180, v180, v179
	v_mul_f32_e32 v181, v181, v166
	v_mul_f32_e32 v62, v62, v180
	v_mul_f32_e32 v63, v63, v181
	v_lshlrev_b32_e32 v178, 16, v163
	v_and_b32_e32 v163, 0xffff0000, v163
	v_lshlrev_b32_e32 v179, 16, v167
	v_and_b32_e32 v167, 0xffff0000, v167
	v_mul_f32_e32 v64, 0xbfb8aa3b, v64
	v_mul_f32_e32 v65, 0xbfb8aa3b, v65
	v_mul_f32_e32 v180, 0xbfb8aa3b, v179
	v_mul_f32_e32 v181, 0xbfb8aa3b, v167
	v_exp_f32_e32 v64, v64
	v_exp_f32_e32 v65, v65
	v_exp_f32_e32 v180, v180
	v_exp_f32_e32 v181, v181
	v_add_f32_e32 v64, 1.0, v64
	v_add_f32_e32 v65, 1.0, v65
	v_add_f32_e32 v180, 1.0, v180
	v_add_f32_e32 v181, 1.0, v181
	v_rcp_f32_e32 v64, v64
	v_rcp_f32_e32 v65, v65
	v_rcp_f32_e32 v180, v180
	v_rcp_f32_e32 v181, v181
	v_mul_f32_e32 v64, v64, v178
	v_mul_f32_e32 v65, v65, v163
	v_mul_f32_e32 v180, v180, v179
	v_mul_f32_e32 v181, v181, v167
	v_mul_f32_e32 v64, v64, v180
	v_mul_f32_e32 v65, v65, v181
	v_lshlrev_b32_e32 v178, 16, v164
	v_and_b32_e32 v164, 0xffff0000, v164
	v_lshlrev_b32_e32 v179, 16, v168
	v_and_b32_e32 v168, 0xffff0000, v168
	v_mul_f32_e32 v58, 0xbfb8aa3b, v58
	v_mul_f32_e32 v59, 0xbfb8aa3b, v59
	v_mul_f32_e32 v180, 0xbfb8aa3b, v179
	v_mul_f32_e32 v181, 0xbfb8aa3b, v168
	v_exp_f32_e32 v58, v58
	v_exp_f32_e32 v59, v59
	v_exp_f32_e32 v180, v180
	v_exp_f32_e32 v181, v181
	v_add_f32_e32 v58, 1.0, v58
	v_add_f32_e32 v59, 1.0, v59
	v_add_f32_e32 v180, 1.0, v180
	v_add_f32_e32 v181, 1.0, v181
	v_rcp_f32_e32 v58, v58
	v_rcp_f32_e32 v59, v59
	v_rcp_f32_e32 v180, v180
	v_rcp_f32_e32 v181, v181
	v_mul_f32_e32 v58, v58, v178
	v_mul_f32_e32 v59, v59, v164
	v_mul_f32_e32 v180, v180, v179
	v_mul_f32_e32 v181, v181, v168
	v_mul_f32_e32 v58, v58, v180
	v_mul_f32_e32 v59, v59, v181
	v_lshlrev_b32_e32 v178, 16, v165
	v_and_b32_e32 v165, 0xffff0000, v165
	v_lshlrev_b32_e32 v179, 16, v169
	v_and_b32_e32 v169, 0xffff0000, v169
	v_mul_f32_e32 v60, 0xbfb8aa3b, v60
	v_mul_f32_e32 v61, 0xbfb8aa3b, v61
	v_mul_f32_e32 v180, 0xbfb8aa3b, v179
	v_mul_f32_e32 v181, 0xbfb8aa3b, v169
	v_exp_f32_e32 v60, v60
	v_exp_f32_e32 v61, v61
	v_exp_f32_e32 v180, v180
	v_exp_f32_e32 v181, v181
	v_add_f32_e32 v60, 1.0, v60
	v_add_f32_e32 v61, 1.0, v61
	v_add_f32_e32 v180, 1.0, v180
	v_add_f32_e32 v181, 1.0, v181
	v_rcp_f32_e32 v60, v60
	v_rcp_f32_e32 v61, v61
	v_rcp_f32_e32 v180, v180
	v_rcp_f32_e32 v181, v181
	v_mul_f32_e32 v60, v60, v178
	v_mul_f32_e32 v61, v61, v165
	v_mul_f32_e32 v180, v180, v179
	v_mul_f32_e32 v181, v181, v169
	v_mul_f32_e32 v60, v60, v180
	v_mul_f32_e32 v61, v61, v181
	v_cvt_pk_bf16_f32 v62, v62, v63
	v_cvt_pk_bf16_f32 v63, v64, v65
	v_cvt_pk_bf16_f32 v64, v58, v59
	v_cvt_pk_bf16_f32 v65, v60, v61
	global_store_dwordx4 v[146:147], v[62:65], off
	global_load_dwordx4 v[162:165], v[142:143], off offset:256
	global_load_dwordx4 v[166:169], v[144:145], off offset:256
	s_waitcnt vmcnt(6)
	v_lshlrev_b32_e32 v178, 16, v170
	v_and_b32_e32 v170, 0xffff0000, v170
	v_lshlrev_b32_e32 v179, 16, v174
	v_and_b32_e32 v174, 0xffff0000, v174
	v_mul_f32_e32 v54, 0xbfb8aa3b, v54
	v_mul_f32_e32 v55, 0xbfb8aa3b, v55
	v_mul_f32_e32 v180, 0xbfb8aa3b, v179
	v_mul_f32_e32 v181, 0xbfb8aa3b, v174
	v_exp_f32_e32 v54, v54
	v_exp_f32_e32 v55, v55
	v_exp_f32_e32 v180, v180
	v_exp_f32_e32 v181, v181
	v_add_f32_e32 v54, 1.0, v54
	v_add_f32_e32 v55, 1.0, v55
	v_add_f32_e32 v180, 1.0, v180
	v_add_f32_e32 v181, 1.0, v181
	v_rcp_f32_e32 v54, v54
	v_rcp_f32_e32 v55, v55
	v_rcp_f32_e32 v180, v180
	v_rcp_f32_e32 v181, v181
	v_mul_f32_e32 v54, v54, v178
	v_mul_f32_e32 v55, v55, v170
	v_mul_f32_e32 v180, v180, v179
	v_mul_f32_e32 v181, v181, v174
	v_mul_f32_e32 v54, v54, v180
	v_mul_f32_e32 v55, v55, v181
	v_lshlrev_b32_e32 v178, 16, v171
	v_and_b32_e32 v171, 0xffff0000, v171
	v_lshlrev_b32_e32 v179, 16, v175
	v_and_b32_e32 v175, 0xffff0000, v175
	v_mul_f32_e32 v56, 0xbfb8aa3b, v56
	v_mul_f32_e32 v57, 0xbfb8aa3b, v57
	v_mul_f32_e32 v180, 0xbfb8aa3b, v179
	v_mul_f32_e32 v181, 0xbfb8aa3b, v175
	v_exp_f32_e32 v56, v56
	v_exp_f32_e32 v57, v57
	v_exp_f32_e32 v180, v180
	v_exp_f32_e32 v181, v181
	v_add_f32_e32 v56, 1.0, v56
	v_add_f32_e32 v57, 1.0, v57
	v_add_f32_e32 v180, 1.0, v180
	v_add_f32_e32 v181, 1.0, v181
	v_rcp_f32_e32 v56, v56
	v_rcp_f32_e32 v57, v57
	v_rcp_f32_e32 v180, v180
	v_rcp_f32_e32 v181, v181
	v_mul_f32_e32 v56, v56, v178
	v_mul_f32_e32 v57, v57, v171
	v_mul_f32_e32 v180, v180, v179
	v_mul_f32_e32 v181, v181, v175
	v_mul_f32_e32 v56, v56, v180
	v_mul_f32_e32 v57, v57, v181
	v_lshlrev_b32_e32 v178, 16, v172
	v_and_b32_e32 v172, 0xffff0000, v172
	v_lshlrev_b32_e32 v179, 16, v176
	v_and_b32_e32 v176, 0xffff0000, v176
	v_mul_f32_e32 v50, 0xbfb8aa3b, v50
	v_mul_f32_e32 v51, 0xbfb8aa3b, v51
	v_mul_f32_e32 v180, 0xbfb8aa3b, v179
	v_mul_f32_e32 v181, 0xbfb8aa3b, v176
	v_exp_f32_e32 v50, v50
	v_exp_f32_e32 v51, v51
	v_exp_f32_e32 v180, v180
	v_exp_f32_e32 v181, v181
	v_add_f32_e32 v50, 1.0, v50
	v_add_f32_e32 v51, 1.0, v51
	v_add_f32_e32 v180, 1.0, v180
	v_add_f32_e32 v181, 1.0, v181
	v_rcp_f32_e32 v50, v50
	v_rcp_f32_e32 v51, v51
	v_rcp_f32_e32 v180, v180
	v_rcp_f32_e32 v181, v181
	v_mul_f32_e32 v50, v50, v178
	v_mul_f32_e32 v51, v51, v172
	v_mul_f32_e32 v180, v180, v179
	v_mul_f32_e32 v181, v181, v176
	v_mul_f32_e32 v50, v50, v180
	v_mul_f32_e32 v51, v51, v181
	v_lshlrev_b32_e32 v178, 16, v173
	v_and_b32_e32 v173, 0xffff0000, v173
	v_lshlrev_b32_e32 v179, 16, v177
	v_and_b32_e32 v177, 0xffff0000, v177
	v_mul_f32_e32 v52, 0xbfb8aa3b, v52
	v_mul_f32_e32 v53, 0xbfb8aa3b, v53
	v_mul_f32_e32 v180, 0xbfb8aa3b, v179
	v_mul_f32_e32 v181, 0xbfb8aa3b, v177
	v_exp_f32_e32 v52, v52
	v_exp_f32_e32 v53, v53
	v_exp_f32_e32 v180, v180
	v_exp_f32_e32 v181, v181
	v_add_f32_e32 v52, 1.0, v52
	v_add_f32_e32 v53, 1.0, v53
	v_add_f32_e32 v180, 1.0, v180
	v_add_f32_e32 v181, 1.0, v181
	v_rcp_f32_e32 v52, v52
	v_rcp_f32_e32 v53, v53
	v_rcp_f32_e32 v180, v180
	v_rcp_f32_e32 v181, v181
	v_mul_f32_e32 v52, v52, v178
	v_mul_f32_e32 v53, v53, v173
	v_mul_f32_e32 v180, v180, v179
	v_mul_f32_e32 v181, v181, v177
	v_mul_f32_e32 v52, v52, v180
	v_mul_f32_e32 v53, v53, v181
	v_cvt_pk_bf16_f32 v54, v54, v55
	v_cvt_pk_bf16_f32 v55, v56, v57
	v_cvt_pk_bf16_f32 v56, v50, v51
	v_cvt_pk_bf16_f32 v57, v52, v53
	global_store_dwordx4 v[146:147], v[54:57], off offset:256
	s_mov_b64 s[58:59], 0x20000
	v_lshl_add_u64 v[146:147], v[146:147], 0, s[58:59]
	s_mov_b64 s[58:59], 0x8000
	v_lshl_add_u64 v[142:143], v[142:143], 0, s[58:59]
	s_mov_b64 s[58:59], 0x4000
	v_lshl_add_u64 v[144:145], v[144:145], 0, s[58:59]
	global_load_dwordx4 v[170:173], v[142:143], off
	global_load_dwordx4 v[174:177], v[144:145], off
	s_waitcnt vmcnt(6)
	v_lshlrev_b32_e32 v178, 16, v154
	v_and_b32_e32 v154, 0xffff0000, v154
	v_lshlrev_b32_e32 v179, 16, v158
	v_and_b32_e32 v158, 0xffff0000, v158
	v_mul_f32_e32 v46, 0xbfb8aa3b, v46
	v_mul_f32_e32 v47, 0xbfb8aa3b, v47
	v_mul_f32_e32 v180, 0xbfb8aa3b, v179
	v_mul_f32_e32 v181, 0xbfb8aa3b, v158
	v_exp_f32_e32 v46, v46
	v_exp_f32_e32 v47, v47
	v_exp_f32_e32 v180, v180
	v_exp_f32_e32 v181, v181
	v_add_f32_e32 v46, 1.0, v46
	v_add_f32_e32 v47, 1.0, v47
	v_add_f32_e32 v180, 1.0, v180
	v_add_f32_e32 v181, 1.0, v181
	v_rcp_f32_e32 v46, v46
	v_rcp_f32_e32 v47, v47
	v_rcp_f32_e32 v180, v180
	v_rcp_f32_e32 v181, v181
	v_mul_f32_e32 v46, v46, v178
	v_mul_f32_e32 v47, v47, v154
	v_mul_f32_e32 v180, v180, v179
	v_mul_f32_e32 v181, v181, v158
	v_mul_f32_e32 v46, v46, v180
	v_mul_f32_e32 v47, v47, v181
	v_lshlrev_b32_e32 v178, 16, v155
	v_and_b32_e32 v155, 0xffff0000, v155
	v_lshlrev_b32_e32 v179, 16, v159
	v_and_b32_e32 v159, 0xffff0000, v159
	v_mul_f32_e32 v48, 0xbfb8aa3b, v48
	v_mul_f32_e32 v49, 0xbfb8aa3b, v49
	v_mul_f32_e32 v180, 0xbfb8aa3b, v179
	v_mul_f32_e32 v181, 0xbfb8aa3b, v159
	v_exp_f32_e32 v48, v48
	v_exp_f32_e32 v49, v49
	v_exp_f32_e32 v180, v180
	v_exp_f32_e32 v181, v181
	v_add_f32_e32 v48, 1.0, v48
	v_add_f32_e32 v49, 1.0, v49
	v_add_f32_e32 v180, 1.0, v180
	v_add_f32_e32 v181, 1.0, v181
	v_rcp_f32_e32 v48, v48
	v_rcp_f32_e32 v49, v49
	v_rcp_f32_e32 v180, v180
	v_rcp_f32_e32 v181, v181
	v_mul_f32_e32 v48, v48, v178
	v_mul_f32_e32 v49, v49, v155
	v_mul_f32_e32 v180, v180, v179
	v_mul_f32_e32 v181, v181, v159
	v_mul_f32_e32 v48, v48, v180
	v_mul_f32_e32 v49, v49, v181
	v_lshlrev_b32_e32 v178, 16, v156
	v_and_b32_e32 v156, 0xffff0000, v156
	v_lshlrev_b32_e32 v179, 16, v160
	v_and_b32_e32 v160, 0xffff0000, v160
	v_mul_f32_e32 v42, 0xbfb8aa3b, v42
	v_mul_f32_e32 v43, 0xbfb8aa3b, v43
	v_mul_f32_e32 v180, 0xbfb8aa3b, v179
	v_mul_f32_e32 v181, 0xbfb8aa3b, v160
	v_exp_f32_e32 v42, v42
	v_exp_f32_e32 v43, v43
	v_exp_f32_e32 v180, v180
	v_exp_f32_e32 v181, v181
	v_add_f32_e32 v42, 1.0, v42
	v_add_f32_e32 v43, 1.0, v43
	v_add_f32_e32 v180, 1.0, v180
	v_add_f32_e32 v181, 1.0, v181
	v_rcp_f32_e32 v42, v42
	v_rcp_f32_e32 v43, v43
	v_rcp_f32_e32 v180, v180
	v_rcp_f32_e32 v181, v181
	v_mul_f32_e32 v42, v42, v178
	v_mul_f32_e32 v43, v43, v156
	v_mul_f32_e32 v180, v180, v179
	v_mul_f32_e32 v181, v181, v160
	v_mul_f32_e32 v42, v42, v180
	v_mul_f32_e32 v43, v43, v181
	v_lshlrev_b32_e32 v178, 16, v157
	v_and_b32_e32 v157, 0xffff0000, v157
	v_lshlrev_b32_e32 v179, 16, v161
	v_and_b32_e32 v161, 0xffff0000, v161
	v_mul_f32_e32 v44, 0xbfb8aa3b, v44
	v_mul_f32_e32 v45, 0xbfb8aa3b, v45
	v_mul_f32_e32 v180, 0xbfb8aa3b, v179
	v_mul_f32_e32 v181, 0xbfb8aa3b, v161
	v_exp_f32_e32 v44, v44
	v_exp_f32_e32 v45, v45
	v_exp_f32_e32 v180, v180
	v_exp_f32_e32 v181, v181
	v_add_f32_e32 v44, 1.0, v44
	v_add_f32_e32 v45, 1.0, v45
	v_add_f32_e32 v180, 1.0, v180
	v_add_f32_e32 v181, 1.0, v181
	v_rcp_f32_e32 v44, v44
	v_rcp_f32_e32 v45, v45
	v_rcp_f32_e32 v180, v180
	v_rcp_f32_e32 v181, v181
	v_mul_f32_e32 v44, v44, v178
	v_mul_f32_e32 v45, v45, v157
	v_mul_f32_e32 v180, v180, v179
	v_mul_f32_e32 v181, v181, v161
	v_mul_f32_e32 v44, v44, v180
	v_mul_f32_e32 v45, v45, v181
	v_cvt_pk_bf16_f32 v46, v46, v47
	v_cvt_pk_bf16_f32 v47, v48, v49
	v_cvt_pk_bf16_f32 v48, v42, v43
	v_cvt_pk_bf16_f32 v49, v44, v45
	global_store_dwordx4 v[146:147], v[46:49], off
	global_load_dwordx4 v[154:157], v[142:143], off offset:256
	global_load_dwordx4 v[158:161], v[144:145], off offset:256
	s_waitcnt vmcnt(6)
	v_lshlrev_b32_e32 v178, 16, v162
	v_and_b32_e32 v162, 0xffff0000, v162
	v_lshlrev_b32_e32 v179, 16, v166
	v_and_b32_e32 v166, 0xffff0000, v166
	v_mul_f32_e32 v38, 0xbfb8aa3b, v38
	v_mul_f32_e32 v39, 0xbfb8aa3b, v39
	v_mul_f32_e32 v180, 0xbfb8aa3b, v179
	v_mul_f32_e32 v181, 0xbfb8aa3b, v166
	v_exp_f32_e32 v38, v38
	v_exp_f32_e32 v39, v39
	v_exp_f32_e32 v180, v180
	v_exp_f32_e32 v181, v181
	v_add_f32_e32 v38, 1.0, v38
	v_add_f32_e32 v39, 1.0, v39
	v_add_f32_e32 v180, 1.0, v180
	v_add_f32_e32 v181, 1.0, v181
	v_rcp_f32_e32 v38, v38
	v_rcp_f32_e32 v39, v39
	v_rcp_f32_e32 v180, v180
	v_rcp_f32_e32 v181, v181
	v_mul_f32_e32 v38, v38, v178
	v_mul_f32_e32 v39, v39, v162
	v_mul_f32_e32 v180, v180, v179
	v_mul_f32_e32 v181, v181, v166
	v_mul_f32_e32 v38, v38, v180
	v_mul_f32_e32 v39, v39, v181
	v_lshlrev_b32_e32 v178, 16, v163
	v_and_b32_e32 v163, 0xffff0000, v163
	v_lshlrev_b32_e32 v179, 16, v167
	v_and_b32_e32 v167, 0xffff0000, v167
	v_mul_f32_e32 v40, 0xbfb8aa3b, v40
	v_mul_f32_e32 v41, 0xbfb8aa3b, v41
	v_mul_f32_e32 v180, 0xbfb8aa3b, v179
	v_mul_f32_e32 v181, 0xbfb8aa3b, v167
	v_exp_f32_e32 v40, v40
	v_exp_f32_e32 v41, v41
	v_exp_f32_e32 v180, v180
	v_exp_f32_e32 v181, v181
	v_add_f32_e32 v40, 1.0, v40
	v_add_f32_e32 v41, 1.0, v41
	v_add_f32_e32 v180, 1.0, v180
	v_add_f32_e32 v181, 1.0, v181
	v_rcp_f32_e32 v40, v40
	v_rcp_f32_e32 v41, v41
	v_rcp_f32_e32 v180, v180
	v_rcp_f32_e32 v181, v181
	v_mul_f32_e32 v40, v40, v178
	v_mul_f32_e32 v41, v41, v163
	v_mul_f32_e32 v180, v180, v179
	v_mul_f32_e32 v181, v181, v167
	v_mul_f32_e32 v40, v40, v180
	v_mul_f32_e32 v41, v41, v181
	v_lshlrev_b32_e32 v178, 16, v164
	v_and_b32_e32 v164, 0xffff0000, v164
	v_lshlrev_b32_e32 v179, 16, v168
	v_and_b32_e32 v168, 0xffff0000, v168
	v_mul_f32_e32 v34, 0xbfb8aa3b, v34
	v_mul_f32_e32 v35, 0xbfb8aa3b, v35
	v_mul_f32_e32 v180, 0xbfb8aa3b, v179
	v_mul_f32_e32 v181, 0xbfb8aa3b, v168
	v_exp_f32_e32 v34, v34
	v_exp_f32_e32 v35, v35
	v_exp_f32_e32 v180, v180
	v_exp_f32_e32 v181, v181
	v_add_f32_e32 v34, 1.0, v34
	v_add_f32_e32 v35, 1.0, v35
	v_add_f32_e32 v180, 1.0, v180
	v_add_f32_e32 v181, 1.0, v181
	v_rcp_f32_e32 v34, v34
	v_rcp_f32_e32 v35, v35
	v_rcp_f32_e32 v180, v180
	v_rcp_f32_e32 v181, v181
	v_mul_f32_e32 v34, v34, v178
	v_mul_f32_e32 v35, v35, v164
	v_mul_f32_e32 v180, v180, v179
	v_mul_f32_e32 v181, v181, v168
	v_mul_f32_e32 v34, v34, v180
	v_mul_f32_e32 v35, v35, v181
	v_lshlrev_b32_e32 v178, 16, v165
	v_and_b32_e32 v165, 0xffff0000, v165
	v_lshlrev_b32_e32 v179, 16, v169
	v_and_b32_e32 v169, 0xffff0000, v169
	v_mul_f32_e32 v36, 0xbfb8aa3b, v36
	v_mul_f32_e32 v37, 0xbfb8aa3b, v37
	v_mul_f32_e32 v180, 0xbfb8aa3b, v179
	v_mul_f32_e32 v181, 0xbfb8aa3b, v169
	v_exp_f32_e32 v36, v36
	v_exp_f32_e32 v37, v37
	v_exp_f32_e32 v180, v180
	v_exp_f32_e32 v181, v181
	v_add_f32_e32 v36, 1.0, v36
	v_add_f32_e32 v37, 1.0, v37
	v_add_f32_e32 v180, 1.0, v180
	v_add_f32_e32 v181, 1.0, v181
	v_rcp_f32_e32 v36, v36
	v_rcp_f32_e32 v37, v37
	v_rcp_f32_e32 v180, v180
	v_rcp_f32_e32 v181, v181
	v_mul_f32_e32 v36, v36, v178
	v_mul_f32_e32 v37, v37, v165
	v_mul_f32_e32 v180, v180, v179
	v_mul_f32_e32 v181, v181, v169
	v_mul_f32_e32 v36, v36, v180
	v_mul_f32_e32 v37, v37, v181
	v_cvt_pk_bf16_f32 v38, v38, v39
	v_cvt_pk_bf16_f32 v39, v40, v41
	v_cvt_pk_bf16_f32 v40, v34, v35
	v_cvt_pk_bf16_f32 v41, v36, v37
	global_store_dwordx4 v[146:147], v[38:41], off offset:256
	s_mov_b64 s[58:59], 0x20000
	v_lshl_add_u64 v[146:147], v[146:147], 0, s[58:59]
	s_mov_b64 s[58:59], 0x8000
	v_lshl_add_u64 v[142:143], v[142:143], 0, s[58:59]
	s_mov_b64 s[58:59], 0x4000
	v_lshl_add_u64 v[144:145], v[144:145], 0, s[58:59]
	global_load_dwordx4 v[162:165], v[142:143], off
	global_load_dwordx4 v[166:169], v[144:145], off
	s_waitcnt vmcnt(6)
	v_lshlrev_b32_e32 v178, 16, v170
	v_and_b32_e32 v170, 0xffff0000, v170
	v_lshlrev_b32_e32 v179, 16, v174
	v_and_b32_e32 v174, 0xffff0000, v174
	v_mul_f32_e32 v30, 0xbfb8aa3b, v30
	v_mul_f32_e32 v31, 0xbfb8aa3b, v31
	v_mul_f32_e32 v180, 0xbfb8aa3b, v179
	v_mul_f32_e32 v181, 0xbfb8aa3b, v174
	v_exp_f32_e32 v30, v30
	v_exp_f32_e32 v31, v31
	v_exp_f32_e32 v180, v180
	v_exp_f32_e32 v181, v181
	v_add_f32_e32 v30, 1.0, v30
	v_add_f32_e32 v31, 1.0, v31
	v_add_f32_e32 v180, 1.0, v180
	v_add_f32_e32 v181, 1.0, v181
	v_rcp_f32_e32 v30, v30
	v_rcp_f32_e32 v31, v31
	v_rcp_f32_e32 v180, v180
	v_rcp_f32_e32 v181, v181
	v_mul_f32_e32 v30, v30, v178
	v_mul_f32_e32 v31, v31, v170
	v_mul_f32_e32 v180, v180, v179
	v_mul_f32_e32 v181, v181, v174
	v_mul_f32_e32 v30, v30, v180
	v_mul_f32_e32 v31, v31, v181
	v_lshlrev_b32_e32 v178, 16, v171
	v_and_b32_e32 v171, 0xffff0000, v171
	v_lshlrev_b32_e32 v179, 16, v175
	v_and_b32_e32 v175, 0xffff0000, v175
	v_mul_f32_e32 v32, 0xbfb8aa3b, v32
	v_mul_f32_e32 v33, 0xbfb8aa3b, v33
	v_mul_f32_e32 v180, 0xbfb8aa3b, v179
	v_mul_f32_e32 v181, 0xbfb8aa3b, v175
	v_exp_f32_e32 v32, v32
	v_exp_f32_e32 v33, v33
	v_exp_f32_e32 v180, v180
	v_exp_f32_e32 v181, v181
	v_add_f32_e32 v32, 1.0, v32
	v_add_f32_e32 v33, 1.0, v33
	v_add_f32_e32 v180, 1.0, v180
	v_add_f32_e32 v181, 1.0, v181
	v_rcp_f32_e32 v32, v32
	v_rcp_f32_e32 v33, v33
	v_rcp_f32_e32 v180, v180
	v_rcp_f32_e32 v181, v181
	v_mul_f32_e32 v32, v32, v178
	v_mul_f32_e32 v33, v33, v171
	v_mul_f32_e32 v180, v180, v179
	v_mul_f32_e32 v181, v181, v175
	v_mul_f32_e32 v32, v32, v180
	v_mul_f32_e32 v33, v33, v181
	v_lshlrev_b32_e32 v178, 16, v172
	v_and_b32_e32 v172, 0xffff0000, v172
	v_lshlrev_b32_e32 v179, 16, v176
	v_and_b32_e32 v176, 0xffff0000, v176
	v_mul_f32_e32 v26, 0xbfb8aa3b, v26
	v_mul_f32_e32 v27, 0xbfb8aa3b, v27
	v_mul_f32_e32 v180, 0xbfb8aa3b, v179
	v_mul_f32_e32 v181, 0xbfb8aa3b, v176
	v_exp_f32_e32 v26, v26
	v_exp_f32_e32 v27, v27
	v_exp_f32_e32 v180, v180
	v_exp_f32_e32 v181, v181
	v_add_f32_e32 v26, 1.0, v26
	v_add_f32_e32 v27, 1.0, v27
	v_add_f32_e32 v180, 1.0, v180
	v_add_f32_e32 v181, 1.0, v181
	v_rcp_f32_e32 v26, v26
	v_rcp_f32_e32 v27, v27
	v_rcp_f32_e32 v180, v180
	v_rcp_f32_e32 v181, v181
	v_mul_f32_e32 v26, v26, v178
	v_mul_f32_e32 v27, v27, v172
	v_mul_f32_e32 v180, v180, v179
	v_mul_f32_e32 v181, v181, v176
	v_mul_f32_e32 v26, v26, v180
	v_mul_f32_e32 v27, v27, v181
	v_lshlrev_b32_e32 v178, 16, v173
	v_and_b32_e32 v173, 0xffff0000, v173
	v_lshlrev_b32_e32 v179, 16, v177
	v_and_b32_e32 v177, 0xffff0000, v177
	v_mul_f32_e32 v28, 0xbfb8aa3b, v28
	v_mul_f32_e32 v29, 0xbfb8aa3b, v29
	v_mul_f32_e32 v180, 0xbfb8aa3b, v179
	v_mul_f32_e32 v181, 0xbfb8aa3b, v177
	v_exp_f32_e32 v28, v28
	v_exp_f32_e32 v29, v29
	v_exp_f32_e32 v180, v180
	v_exp_f32_e32 v181, v181
	v_add_f32_e32 v28, 1.0, v28
	v_add_f32_e32 v29, 1.0, v29
	v_add_f32_e32 v180, 1.0, v180
	v_add_f32_e32 v181, 1.0, v181
	v_rcp_f32_e32 v28, v28
	v_rcp_f32_e32 v29, v29
	v_rcp_f32_e32 v180, v180
	v_rcp_f32_e32 v181, v181
	v_mul_f32_e32 v28, v28, v178
	v_mul_f32_e32 v29, v29, v173
	v_mul_f32_e32 v180, v180, v179
	v_mul_f32_e32 v181, v181, v177
	v_mul_f32_e32 v28, v28, v180
	v_mul_f32_e32 v29, v29, v181
	v_cvt_pk_bf16_f32 v30, v30, v31
	v_cvt_pk_bf16_f32 v31, v32, v33
	v_cvt_pk_bf16_f32 v32, v26, v27
	v_cvt_pk_bf16_f32 v33, v28, v29
	global_store_dwordx4 v[146:147], v[30:33], off
	global_load_dwordx4 v[170:173], v[142:143], off offset:256
	global_load_dwordx4 v[174:177], v[144:145], off offset:256
	s_waitcnt vmcnt(6)
	v_lshlrev_b32_e32 v178, 16, v154
	v_and_b32_e32 v154, 0xffff0000, v154
	v_lshlrev_b32_e32 v179, 16, v158
	v_and_b32_e32 v158, 0xffff0000, v158
	v_mul_f32_e32 v22, 0xbfb8aa3b, v22
	v_mul_f32_e32 v23, 0xbfb8aa3b, v23
	v_mul_f32_e32 v180, 0xbfb8aa3b, v179
	v_mul_f32_e32 v181, 0xbfb8aa3b, v158
	v_exp_f32_e32 v22, v22
	v_exp_f32_e32 v23, v23
	v_exp_f32_e32 v180, v180
	v_exp_f32_e32 v181, v181
	v_add_f32_e32 v22, 1.0, v22
	v_add_f32_e32 v23, 1.0, v23
	v_add_f32_e32 v180, 1.0, v180
	v_add_f32_e32 v181, 1.0, v181
	v_rcp_f32_e32 v22, v22
	v_rcp_f32_e32 v23, v23
	v_rcp_f32_e32 v180, v180
	v_rcp_f32_e32 v181, v181
	v_mul_f32_e32 v22, v22, v178
	v_mul_f32_e32 v23, v23, v154
	v_mul_f32_e32 v180, v180, v179
	v_mul_f32_e32 v181, v181, v158
	v_mul_f32_e32 v22, v22, v180
	v_mul_f32_e32 v23, v23, v181
	v_lshlrev_b32_e32 v178, 16, v155
	v_and_b32_e32 v155, 0xffff0000, v155
	v_lshlrev_b32_e32 v179, 16, v159
	v_and_b32_e32 v159, 0xffff0000, v159
	v_mul_f32_e32 v24, 0xbfb8aa3b, v24
	v_mul_f32_e32 v25, 0xbfb8aa3b, v25
	v_mul_f32_e32 v180, 0xbfb8aa3b, v179
	v_mul_f32_e32 v181, 0xbfb8aa3b, v159
	v_exp_f32_e32 v24, v24
	v_exp_f32_e32 v25, v25
	v_exp_f32_e32 v180, v180
	v_exp_f32_e32 v181, v181
	v_add_f32_e32 v24, 1.0, v24
	v_add_f32_e32 v25, 1.0, v25
	v_add_f32_e32 v180, 1.0, v180
	v_add_f32_e32 v181, 1.0, v181
	v_rcp_f32_e32 v24, v24
	v_rcp_f32_e32 v25, v25
	v_rcp_f32_e32 v180, v180
	v_rcp_f32_e32 v181, v181
	v_mul_f32_e32 v24, v24, v178
	v_mul_f32_e32 v25, v25, v155
	v_mul_f32_e32 v180, v180, v179
	v_mul_f32_e32 v181, v181, v159
	v_mul_f32_e32 v24, v24, v180
	v_mul_f32_e32 v25, v25, v181
	v_lshlrev_b32_e32 v178, 16, v156
	v_and_b32_e32 v156, 0xffff0000, v156
	v_lshlrev_b32_e32 v179, 16, v160
	v_and_b32_e32 v160, 0xffff0000, v160
	v_mul_f32_e32 v18, 0xbfb8aa3b, v18
	v_mul_f32_e32 v19, 0xbfb8aa3b, v19
	v_mul_f32_e32 v180, 0xbfb8aa3b, v179
	v_mul_f32_e32 v181, 0xbfb8aa3b, v160
	v_exp_f32_e32 v18, v18
	v_exp_f32_e32 v19, v19
	v_exp_f32_e32 v180, v180
	v_exp_f32_e32 v181, v181
	v_add_f32_e32 v18, 1.0, v18
	v_add_f32_e32 v19, 1.0, v19
	v_add_f32_e32 v180, 1.0, v180
	v_add_f32_e32 v181, 1.0, v181
	v_rcp_f32_e32 v18, v18
	v_rcp_f32_e32 v19, v19
	v_rcp_f32_e32 v180, v180
	v_rcp_f32_e32 v181, v181
	v_mul_f32_e32 v18, v18, v178
	v_mul_f32_e32 v19, v19, v156
	v_mul_f32_e32 v180, v180, v179
	v_mul_f32_e32 v181, v181, v160
	v_mul_f32_e32 v18, v18, v180
	v_mul_f32_e32 v19, v19, v181
	v_lshlrev_b32_e32 v178, 16, v157
	v_and_b32_e32 v157, 0xffff0000, v157
	v_lshlrev_b32_e32 v179, 16, v161
	v_and_b32_e32 v161, 0xffff0000, v161
	v_mul_f32_e32 v20, 0xbfb8aa3b, v20
	v_mul_f32_e32 v21, 0xbfb8aa3b, v21
	v_mul_f32_e32 v180, 0xbfb8aa3b, v179
	v_mul_f32_e32 v181, 0xbfb8aa3b, v161
	v_exp_f32_e32 v20, v20
	v_exp_f32_e32 v21, v21
	v_exp_f32_e32 v180, v180
	v_exp_f32_e32 v181, v181
	v_add_f32_e32 v20, 1.0, v20
	v_add_f32_e32 v21, 1.0, v21
	v_add_f32_e32 v180, 1.0, v180
	v_add_f32_e32 v181, 1.0, v181
	v_rcp_f32_e32 v20, v20
	v_rcp_f32_e32 v21, v21
	v_rcp_f32_e32 v180, v180
	v_rcp_f32_e32 v181, v181
	v_mul_f32_e32 v20, v20, v178
	v_mul_f32_e32 v21, v21, v157
	v_mul_f32_e32 v180, v180, v179
	v_mul_f32_e32 v181, v181, v161
	v_mul_f32_e32 v20, v20, v180
	v_mul_f32_e32 v21, v21, v181
	v_cvt_pk_bf16_f32 v22, v22, v23
	v_cvt_pk_bf16_f32 v23, v24, v25
	v_cvt_pk_bf16_f32 v24, v18, v19
	v_cvt_pk_bf16_f32 v25, v20, v21
	global_store_dwordx4 v[146:147], v[22:25], off offset:256
	s_mov_b64 s[58:59], 0x20000
	v_lshl_add_u64 v[146:147], v[146:147], 0, s[58:59]
	s_waitcnt vmcnt(4)
	v_lshlrev_b32_e32 v178, 16, v162
	v_and_b32_e32 v162, 0xffff0000, v162
	v_lshlrev_b32_e32 v179, 16, v166
	v_and_b32_e32 v166, 0xffff0000, v166
	v_mul_f32_e32 v14, 0xbfb8aa3b, v14
	v_mul_f32_e32 v15, 0xbfb8aa3b, v15
	v_mul_f32_e32 v180, 0xbfb8aa3b, v179
	v_mul_f32_e32 v181, 0xbfb8aa3b, v166
	v_exp_f32_e32 v14, v14
	v_exp_f32_e32 v15, v15
	v_exp_f32_e32 v180, v180
	v_exp_f32_e32 v181, v181
	v_add_f32_e32 v14, 1.0, v14
	v_add_f32_e32 v15, 1.0, v15
	v_add_f32_e32 v180, 1.0, v180
	v_add_f32_e32 v181, 1.0, v181
	v_rcp_f32_e32 v14, v14
	v_rcp_f32_e32 v15, v15
	v_rcp_f32_e32 v180, v180
	v_rcp_f32_e32 v181, v181
	v_mul_f32_e32 v14, v14, v178
	v_mul_f32_e32 v15, v15, v162
	v_mul_f32_e32 v180, v180, v179
	v_mul_f32_e32 v181, v181, v166
	v_mul_f32_e32 v14, v14, v180
	v_mul_f32_e32 v15, v15, v181
	v_lshlrev_b32_e32 v178, 16, v163
	v_and_b32_e32 v163, 0xffff0000, v163
	v_lshlrev_b32_e32 v179, 16, v167
	v_and_b32_e32 v167, 0xffff0000, v167
	v_mul_f32_e32 v16, 0xbfb8aa3b, v16
	v_mul_f32_e32 v17, 0xbfb8aa3b, v17
	v_mul_f32_e32 v180, 0xbfb8aa3b, v179
	v_mul_f32_e32 v181, 0xbfb8aa3b, v167
	v_exp_f32_e32 v16, v16
	v_exp_f32_e32 v17, v17
	v_exp_f32_e32 v180, v180
	v_exp_f32_e32 v181, v181
	v_add_f32_e32 v16, 1.0, v16
	v_add_f32_e32 v17, 1.0, v17
	v_add_f32_e32 v180, 1.0, v180
	v_add_f32_e32 v181, 1.0, v181
	v_rcp_f32_e32 v16, v16
	v_rcp_f32_e32 v17, v17
	v_rcp_f32_e32 v180, v180
	v_rcp_f32_e32 v181, v181
	v_mul_f32_e32 v16, v16, v178
	v_mul_f32_e32 v17, v17, v163
	v_mul_f32_e32 v180, v180, v179
	v_mul_f32_e32 v181, v181, v167
	v_mul_f32_e32 v16, v16, v180
	v_mul_f32_e32 v17, v17, v181
	v_lshlrev_b32_e32 v178, 16, v164
	v_and_b32_e32 v164, 0xffff0000, v164
	v_lshlrev_b32_e32 v179, 16, v168
	v_and_b32_e32 v168, 0xffff0000, v168
	v_mul_f32_e32 v10, 0xbfb8aa3b, v10
	v_mul_f32_e32 v11, 0xbfb8aa3b, v11
	v_mul_f32_e32 v180, 0xbfb8aa3b, v179
	v_mul_f32_e32 v181, 0xbfb8aa3b, v168
	v_exp_f32_e32 v10, v10
	v_exp_f32_e32 v11, v11
	v_exp_f32_e32 v180, v180
	v_exp_f32_e32 v181, v181
	v_add_f32_e32 v10, 1.0, v10
	v_add_f32_e32 v11, 1.0, v11
	v_add_f32_e32 v180, 1.0, v180
	v_add_f32_e32 v181, 1.0, v181
	v_rcp_f32_e32 v10, v10
	v_rcp_f32_e32 v11, v11
	v_rcp_f32_e32 v180, v180
	v_rcp_f32_e32 v181, v181
	v_mul_f32_e32 v10, v10, v178
	v_mul_f32_e32 v11, v11, v164
	v_mul_f32_e32 v180, v180, v179
	v_mul_f32_e32 v181, v181, v168
	v_mul_f32_e32 v10, v10, v180
	v_mul_f32_e32 v11, v11, v181
	v_lshlrev_b32_e32 v178, 16, v165
	v_and_b32_e32 v165, 0xffff0000, v165
	v_lshlrev_b32_e32 v179, 16, v169
	v_and_b32_e32 v169, 0xffff0000, v169
	v_mul_f32_e32 v12, 0xbfb8aa3b, v12
	v_mul_f32_e32 v13, 0xbfb8aa3b, v13
	v_mul_f32_e32 v180, 0xbfb8aa3b, v179
	v_mul_f32_e32 v181, 0xbfb8aa3b, v169
	v_exp_f32_e32 v12, v12
	v_exp_f32_e32 v13, v13
	v_exp_f32_e32 v180, v180
	v_exp_f32_e32 v181, v181
	v_add_f32_e32 v12, 1.0, v12
	v_add_f32_e32 v13, 1.0, v13
	v_add_f32_e32 v180, 1.0, v180
	v_add_f32_e32 v181, 1.0, v181
	v_rcp_f32_e32 v12, v12
	v_rcp_f32_e32 v13, v13
	v_rcp_f32_e32 v180, v180
	v_rcp_f32_e32 v181, v181
	v_mul_f32_e32 v12, v12, v178
	v_mul_f32_e32 v13, v13, v165
	v_mul_f32_e32 v180, v180, v179
	v_mul_f32_e32 v181, v181, v169
	v_mul_f32_e32 v12, v12, v180
	v_mul_f32_e32 v13, v13, v181
	v_cvt_pk_bf16_f32 v14, v14, v15
	v_cvt_pk_bf16_f32 v15, v16, v17
	v_cvt_pk_bf16_f32 v16, v10, v11
	v_cvt_pk_bf16_f32 v17, v12, v13
	global_store_dwordx4 v[146:147], v[14:17], off
	s_waitcnt vmcnt(2)
	v_lshlrev_b32_e32 v178, 16, v170
	v_and_b32_e32 v170, 0xffff0000, v170
	v_lshlrev_b32_e32 v179, 16, v174
	v_and_b32_e32 v174, 0xffff0000, v174
	v_mul_f32_e32 v6, 0xbfb8aa3b, v6
	v_mul_f32_e32 v7, 0xbfb8aa3b, v7
	v_mul_f32_e32 v180, 0xbfb8aa3b, v179
	v_mul_f32_e32 v181, 0xbfb8aa3b, v174
	v_exp_f32_e32 v6, v6
	v_exp_f32_e32 v7, v7
	v_exp_f32_e32 v180, v180
	v_exp_f32_e32 v181, v181
	v_add_f32_e32 v6, 1.0, v6
	v_add_f32_e32 v7, 1.0, v7
	v_add_f32_e32 v180, 1.0, v180
	v_add_f32_e32 v181, 1.0, v181
	v_rcp_f32_e32 v6, v6
	v_rcp_f32_e32 v7, v7
	v_rcp_f32_e32 v180, v180
	v_rcp_f32_e32 v181, v181
	v_mul_f32_e32 v6, v6, v178
	v_mul_f32_e32 v7, v7, v170
	v_mul_f32_e32 v180, v180, v179
	v_mul_f32_e32 v181, v181, v174
	v_mul_f32_e32 v6, v6, v180
	v_mul_f32_e32 v7, v7, v181
	v_lshlrev_b32_e32 v178, 16, v171
	v_and_b32_e32 v171, 0xffff0000, v171
	v_lshlrev_b32_e32 v179, 16, v175
	v_and_b32_e32 v175, 0xffff0000, v175
	v_mul_f32_e32 v8, 0xbfb8aa3b, v8
	v_mul_f32_e32 v9, 0xbfb8aa3b, v9
	v_mul_f32_e32 v180, 0xbfb8aa3b, v179
	v_mul_f32_e32 v181, 0xbfb8aa3b, v175
	v_exp_f32_e32 v8, v8
	v_exp_f32_e32 v9, v9
	v_exp_f32_e32 v180, v180
	v_exp_f32_e32 v181, v181
	v_add_f32_e32 v8, 1.0, v8
	v_add_f32_e32 v9, 1.0, v9
	v_add_f32_e32 v180, 1.0, v180
	v_add_f32_e32 v181, 1.0, v181
	v_rcp_f32_e32 v8, v8
	v_rcp_f32_e32 v9, v9
	v_rcp_f32_e32 v180, v180
	v_rcp_f32_e32 v181, v181
	v_mul_f32_e32 v8, v8, v178
	v_mul_f32_e32 v9, v9, v171
	v_mul_f32_e32 v180, v180, v179
	v_mul_f32_e32 v181, v181, v175
	v_mul_f32_e32 v8, v8, v180
	v_mul_f32_e32 v9, v9, v181
	v_lshlrev_b32_e32 v178, 16, v172
	v_and_b32_e32 v172, 0xffff0000, v172
	v_lshlrev_b32_e32 v179, 16, v176
	v_and_b32_e32 v176, 0xffff0000, v176
	v_mul_f32_e32 v2, 0xbfb8aa3b, v2
	v_mul_f32_e32 v3, 0xbfb8aa3b, v3
	v_mul_f32_e32 v180, 0xbfb8aa3b, v179
	v_mul_f32_e32 v181, 0xbfb8aa3b, v176
	v_exp_f32_e32 v2, v2
	v_exp_f32_e32 v3, v3
	v_exp_f32_e32 v180, v180
	v_exp_f32_e32 v181, v181
	v_add_f32_e32 v2, 1.0, v2
	v_add_f32_e32 v3, 1.0, v3
	v_add_f32_e32 v180, 1.0, v180
	v_add_f32_e32 v181, 1.0, v181
	v_rcp_f32_e32 v2, v2
	v_rcp_f32_e32 v3, v3
	v_rcp_f32_e32 v180, v180
	v_rcp_f32_e32 v181, v181
	v_mul_f32_e32 v2, v2, v178
	v_mul_f32_e32 v3, v3, v172
	v_mul_f32_e32 v180, v180, v179
	v_mul_f32_e32 v181, v181, v176
	v_mul_f32_e32 v2, v2, v180
	v_mul_f32_e32 v3, v3, v181
	v_lshlrev_b32_e32 v178, 16, v173
	v_and_b32_e32 v173, 0xffff0000, v173
	v_lshlrev_b32_e32 v179, 16, v177
	v_and_b32_e32 v177, 0xffff0000, v177
	v_mul_f32_e32 v4, 0xbfb8aa3b, v4
	v_mul_f32_e32 v5, 0xbfb8aa3b, v5
	v_mul_f32_e32 v180, 0xbfb8aa3b, v179
	v_mul_f32_e32 v181, 0xbfb8aa3b, v177
	v_exp_f32_e32 v4, v4
	v_exp_f32_e32 v5, v5
	v_exp_f32_e32 v180, v180
	v_exp_f32_e32 v181, v181
	v_add_f32_e32 v4, 1.0, v4
	v_add_f32_e32 v5, 1.0, v5
	v_add_f32_e32 v180, 1.0, v180
	v_add_f32_e32 v181, 1.0, v181
	v_rcp_f32_e32 v4, v4
	v_rcp_f32_e32 v5, v5
	v_rcp_f32_e32 v180, v180
	v_rcp_f32_e32 v181, v181
	v_mul_f32_e32 v4, v4, v178
	v_mul_f32_e32 v5, v5, v173
	v_mul_f32_e32 v180, v180, v179
	v_mul_f32_e32 v181, v181, v177
	v_mul_f32_e32 v4, v4, v180
	v_mul_f32_e32 v5, v5, v181
	v_cvt_pk_bf16_f32 v6, v6, v7
	v_cvt_pk_bf16_f32 v7, v8, v9
	v_cvt_pk_bf16_f32 v8, v2, v3
	v_cvt_pk_bf16_f32 v9, v4, v5
	global_store_dwordx4 v[146:147], v[6:9], off offset:256
	s_andn2_b64 vcc, exec, s[38:39]
	s_mov_b64 s[4:5], -1
	s_cbranch_vccnz .LBB0_686
	s_andn2_b64 vcc, exec, s[42:43]
	s_cbranch_vccnz .LBB0_685
	s_barrier
	s_branch .LBB0_685
	s_nop 0
	s_nop 0
	s_nop 0
	s_nop 0
	s_nop 0
	s_nop 0
	s_nop 0
	s_nop 0
	s_nop 0
	s_nop 0
	s_nop 0
	s_nop 0
	s_nop 0
	s_nop 0
	s_nop 0
	s_nop 0
	s_nop 0
	s_nop 0
	s_nop 0
	s_nop 0
	s_nop 0
	s_nop 0
	s_nop 0
	s_nop 0
	s_nop 0
	s_nop 0
	s_nop 0
	s_nop 0
	s_nop 0
	s_nop 0
	s_nop 0
	s_nop 0
	s_nop 0
	s_nop 0
	s_nop 0
	s_nop 0
	s_nop 0
	s_nop 0
	s_nop 0
	s_nop 0
	s_nop 0
	s_nop 0
	s_nop 0
	s_nop 0
	s_nop 0
	s_nop 0
	s_nop 0
	s_nop 0
	s_nop 0
	s_nop 0
	s_nop 0

.LBB0_699:
	s_cmp_lg_u64 s[78:79], 0
	s_cbranch_scc1 .Lmy_f_nocall
	s_cmpk_lg_i32 s3, 0x100
	s_cbranch_scc1 .Lmy_f_nocall
	s_cmpk_lt_i32 s76, 16
	s_cbranch_scc1 .Lmy_f_nocall
	s_cmpk_gt_i32 s76, 0xbf
	s_cbranch_scc1 .Lmy_f_nocall
	s_movk_i32 s101, 0x5a5a
	s_mov_b32 s0, 1
	v_writelane_b32 v255, s0, 8
	s_branch .Lmy_tramp_call
.Lmy_gemv_ret:
	s_mov_b32 s0, 0
	v_writelane_b32 v255, s0, 8
	s_nop 1

	.amdhsa_kernel _Z3fwd4Args
		.amdhsa_group_segment_fixed_size 0
		.amdhsa_private_segment_fixed_size 0
		.amdhsa_kernarg_size 496
		.amdhsa_user_sgpr_count 2
		.amdhsa_user_sgpr_dispatch_ptr 0
		.amdhsa_user_sgpr_queue_ptr 0
		.amdhsa_user_sgpr_kernarg_segment_ptr 1
		.amdhsa_user_sgpr_dispatch_id 0
		.amdhsa_user_sgpr_kernarg_preload_length 0
		.amdhsa_user_sgpr_kernarg_preload_offset 0
		.amdhsa_user_sgpr_private_segment_size 0
		.amdhsa_uses_dynamic_stack 0
		.amdhsa_enable_private_segment 0
		.amdhsa_system_sgpr_workgroup_id_x 1
		.amdhsa_system_sgpr_workgroup_id_y 0
		.amdhsa_system_sgpr_workgroup_id_z 0
		.amdhsa_system_sgpr_workgroup_info 0
		.amdhsa_system_vgpr_workitem_id 0
		.amdhsa_next_free_vgpr 256
		.amdhsa_next_free_sgpr 102
		.amdhsa_accum_offset 256
		.amdhsa_reserve_vcc 1
		.amdhsa_float_round_mode_32 0
		.amdhsa_float_round_mode_16_64 0
		.amdhsa_float_denorm_mode_32 3
		.amdhsa_float_denorm_mode_16_64 3
		.amdhsa_dx10_clamp 1
		.amdhsa_ieee_mode 1
		.amdhsa_fp16_overflow 0
		.amdhsa_tg_split 0
		.amdhsa_exception_fp_ieee_invalid_op 0
		.amdhsa_exception_fp_denorm_src 0
		.amdhsa_exception_fp_ieee_div_zero 0
		.amdhsa_exception_fp_ieee_overflow 0
		.amdhsa_exception_fp_ieee_underflow 0
		.amdhsa_exception_fp_ieee_inexact 0
		.amdhsa_exception_int_div_zero 0
	.end_amdhsa_kernel

amdhsa.kernels:
  - .agpr_count:     0
    .args:
      - .offset:         0
        .size:           240
        .value_kind:     by_value
      - .offset:         240
        .size:           4
        .value_kind:     hidden_block_count_x
      - .offset:         244
        .size:           4
        .value_kind:     hidden_block_count_y
      - .offset:         248
        .size:           4
        .value_kind:     hidden_block_count_z
      - .offset:         252
        .size:           2
        .value_kind:     hidden_group_size_x
      - .offset:         254
        .size:           2
        .value_kind:     hidden_group_size_y
      - .offset:         256
        .size:           2
        .value_kind:     hidden_group_size_z
      - .offset:         258
        .size:           2
        .value_kind:     hidden_remainder_x
      - .offset:         260
        .size:           2
        .value_kind:     hidden_remainder_y
      - .offset:         262
        .size:           2
        .value_kind:     hidden_remainder_z
      - .offset:         280
        .size:           8
        .value_kind:     hidden_global_offset_x
      - .offset:         288
        .size:           8
        .value_kind:     hidden_global_offset_y
      - .offset:         296
        .size:           8
        .value_kind:     hidden_global_offset_z
      - .offset:         304
        .size:           2
        .value_kind:     hidden_grid_dims
      - .offset:         360
        .size:           4
        .value_kind:     hidden_dynamic_lds_size
    .group_segment_fixed_size: 0
    .kernarg_segment_align: 8
    .kernarg_segment_size: 496
    .language:       OpenCL C
    .language_version:
      - 2
      - 0
    .max_flat_workgroup_size: 512
    .name:           _Z3fwd4Args
    .private_segment_fixed_size: 0
    .sgpr_count:     108
    .sgpr_spill_count: 151
    .symbol:         _Z3fwd4Args.kd
    .uniform_work_group_size: 1
    .uses_dynamic_stack: false
    .vgpr_count:     256
    .vgpr_spill_count: 0
    .wavefront_size: 64
